# v37 + gla3 item: the 16 KB per-chunk state image is fetched once per half (each wave one quarter, 4 fully coalesced loads) and shared through a padded LDS image instead of 16 half-line fragment loads
# speedup vs baseline: 1.0120x; 1.0120x over previous
; #define LAS __attribute__((address_space(3)))
; __device__ __forceinline__ int otid() { int t = threadIdx.x; asm volatile("" : "+v"(t)); return t; }
; __device__ __forceinline__ void gla_issue_loads(GlaLoads& L, const bf16_t* proj, int b, int h, int n, int dk, int seg, int t4, bool want_q) {
; #pragma unroll
;     for (int i = 0; i < 16; ++i) { const int rb = n * 64 + seg * 16 + i, rc = rb < TB ? rb : TB - 1; const bf16_t* rp = proj + (size_t)(b * TB + rc) * NPROJ + h * 64 + dk;
;         L.xl[i] = rp[C_GL]; L.xk[i] = rp[C_K]; if (want_q) L.xq[i] = rp[C_Q]; }
; __device__ void gla3_item(const Params& p, int l, int item, LAS unsigned char* lds) {
;     const int t = otid(), half = t >> 8, t4 = t & 255, wv = (t >> 6) & 3, lane = t & 63, fr = lane & 15, fq = lane >> 4;
;     const int pair = item % (GCH / 2), bh = item / (GCH / 2), b = bh >> 2, h = bh & 3, n = pair * 2 + half;
;     bf16_t* proj = (bf16_t*)(p.ws + WS_PROJ);
;     LAS unsigned char* hl = lds + half * GL_HALF;
;     const int dk = t4 & 63, seg = t4 >> 6;
;     GlaLoads L; gla_issue_loads(L, proj, b, h, n, dk, seg, t4, true);
.LBB0_449:
	s_cmpk_gt_i32 s29, 0x1ff
	s_mov_b64 s[10:11], -1
	s_cbranch_scc0 .LBB0_523
	s_add_i32 s10, s29, 0xfe00
	s_and_b32 s11, s10, 0xffff
	s_mul_i32 s14, s11, 0xf83f
	s_lshr_b32 s11, s14, 21
	s_mul_i32 s15, s11, 33
	s_sub_i32 s10, s10, s15
	v_mov_b32_e32 v71, v228
	s_lshl_b32 s10, s10, 1
	s_bfe_u32 s15, s14, 0x20015
	v_ashrrev_i32_e32 v160, 8, v71
	s_and_b32 s10, s10, 0xfffe
	s_lshr_b32 s22, s14, 23
	s_waitcnt vmcnt(0)
	v_add_u32_e32 v2, s10, v160
	s_lshl_b32 s14, s15, 7
	v_and_b32_e32 v149, 63, v71
	s_lshl_b32 s100, s15, 8
	s_add_u32 s100, s3, s100
	s_addc_u32 s101, s18, 0
	v_lshlrev_b32_e32 v250, 2, v149
	global_load_dword v251, v250, s[100:101]
	v_bfe_u32 v74, v71, 6, 2
	v_lshlrev_b32_e32 v70, 6, v2
	s_add_u32 s40, s20, s14
	v_lshl_or_b32 v192, v74, 4, v70
	s_addc_u32 s41, s21, 0
	v_lshlrev_b32_e32 v0, 1, v149
	s_mul_i32 s10, s22, 0x1020
	v_lshl_add_u64 v[4:5], s[40:41], 0, v[0:1]
	v_min_i32_e32 v0, 0x101f, v192
	v_add_u32_e32 v0, s10, v0
	v_or_b32_e32 v189, 1, v192
	s_waitcnt lgkmcnt(0)
	v_mad_i64_i32 v[6:7], s[40:41], v0, s96, v[4:5]
	s_movk_i32 s22, 0x1000
	v_min_i32_e32 v0, 0x101f, v189
	v_add_co_u32_e32 v8, vcc, s22, v6
	v_add_u32_e32 v0, s10, v0
	v_or_b32_e32 v188, 2, v192
	v_addc_co_u32_e32 v9, vcc, 0, v7, vcc
	v_mad_i64_i32 v[10:11], s[40:41], v0, s96, v[4:5]
	v_min_i32_e32 v0, 0x101f, v188
	v_add_co_u32_e32 v12, vcc, s22, v10
	v_add_u32_e32 v0, s10, v0
	v_or_b32_e32 v186, 3, v192
	v_addc_co_u32_e32 v13, vcc, 0, v11, vcc
	v_mad_i64_i32 v[14:15], s[40:41], v0, s96, v[4:5]
	v_min_i32_e32 v0, 0x101f, v186
	global_load_ushort v193, v[8:9], off
	global_load_ushort v191, v[12:13], off
	global_load_ushort v148, v[14:15], off offset:1536
	global_load_ushort v150, v[14:15], off offset:1024
	global_load_ushort v157, v[10:11], off offset:1536
	global_load_ushort v158, v[10:11], off offset:1024
	global_load_ushort v159, v[6:7], off offset:1536
	global_load_ushort v161, v[6:7], off offset:1024
	v_add_co_u32_e32 v6, vcc, s22, v14
	v_add_u32_e32 v0, s10, v0
	v_or_b32_e32 v184, 4, v192
	v_addc_co_u32_e32 v7, vcc, 0, v15, vcc
	v_mad_i64_i32 v[8:9], s[40:41], v0, s96, v[4:5]
	v_min_i32_e32 v0, 0x101f, v184
	v_add_co_u32_e32 v10, vcc, s22, v8
	v_add_u32_e32 v0, s10, v0
	v_or_b32_e32 v182, 5, v192
	v_addc_co_u32_e32 v11, vcc, 0, v9, vcc
	v_mad_i64_i32 v[12:13], s[40:41], v0, s96, v[4:5]
	v_min_i32_e32 v0, 0x101f, v182
	v_add_co_u32_e32 v14, vcc, s22, v12
	v_add_u32_e32 v0, s10, v0
	v_or_b32_e32 v180, 6, v192
	v_addc_co_u32_e32 v15, vcc, 0, v13, vcc
	v_mad_i64_i32 v[16:17], s[40:41], v0, s96, v[4:5]
	v_min_i32_e32 v0, 0x101f, v180
	global_load_ushort v190, v[6:7], off
	global_load_ushort v187, v[10:11], off
	global_load_ushort v185, v[14:15], off
	global_load_ushort v143, v[16:17], off offset:1024
	global_load_ushort v145, v[12:13], off offset:1536
	global_load_ushort v147, v[12:13], off offset:1024
	global_load_ushort v152, v[8:9], off offset:1536
	global_load_ushort v156, v[8:9], off offset:1024
	v_add_co_u32_e32 v6, vcc, s22, v16
	v_add_u32_e32 v0, s10, v0
	v_or_b32_e32 v178, 7, v192
	v_addc_co_u32_e32 v7, vcc, 0, v17, vcc
	v_mad_i64_i32 v[8:9], s[40:41], v0, s96, v[4:5]
	v_min_i32_e32 v0, 0x101f, v178
	v_add_co_u32_e32 v10, vcc, s22, v8
	v_add_u32_e32 v0, s10, v0
	v_or_b32_e32 v176, 8, v192
	v_addc_co_u32_e32 v11, vcc, 0, v9, vcc
	v_mad_i64_i32 v[12:13], s[40:41], v0, s96, v[4:5]
	v_min_i32_e32 v0, 0x101f, v176
	v_add_co_u32_e32 v14, vcc, s22, v12
	v_add_u32_e32 v0, s10, v0
	v_or_b32_e32 v173, 9, v192
	v_addc_co_u32_e32 v15, vcc, 0, v13, vcc
	global_load_ushort v183, v[6:7], off
	global_load_ushort v181, v[10:11], off
	global_load_ushort v179, v[14:15], off
	global_load_ushort v134, v[12:13], off offset:1536
	global_load_ushort v136, v[12:13], off offset:1024
	global_load_ushort v138, v[8:9], off offset:1536
	global_load_ushort v140, v[8:9], off offset:1024
	global_load_ushort v146, v[16:17], off offset:1536
	v_mad_i64_i32 v[6:7], s[40:41], v0, s96, v[4:5]
	v_min_i32_e32 v0, 0x101f, v173
	v_add_co_u32_e32 v8, vcc, s22, v6
	v_add_u32_e32 v0, s10, v0
	v_or_b32_e32 v172, 10, v192
	v_addc_co_u32_e32 v9, vcc, 0, v7, vcc
	v_mad_i64_i32 v[10:11], s[40:41], v0, s96, v[4:5]
	v_min_i32_e32 v0, 0x101f, v172
	v_add_co_u32_e32 v12, vcc, s22, v10
	v_add_u32_e32 v0, s10, v0
	v_or_b32_e32 v170, 11, v192
	v_addc_co_u32_e32 v13, vcc, 0, v11, vcc
	v_mad_i64_i32 v[14:15], s[40:41], v0, s96, v[4:5]
	v_min_i32_e32 v0, 0x101f, v170
	global_load_ushort v177, v[8:9], off
	global_load_ushort v175, v[12:13], off
	global_load_ushort v121, v[14:15], off offset:1536
	global_load_ushort v125, v[14:15], off offset:1024
	global_load_ushort v128, v[10:11], off offset:1536
	global_load_ushort v133, v[10:11], off offset:1024
	global_load_ushort v135, v[6:7], off offset:1536
	global_load_ushort v137, v[6:7], off offset:1024
	v_add_co_u32_e32 v6, vcc, s22, v14
	v_add_u32_e32 v0, s10, v0
	v_or_b32_e32 v168, 12, v192
	v_addc_co_u32_e32 v7, vcc, 0, v15, vcc
	v_mad_i64_i32 v[8:9], s[40:41], v0, s96, v[4:5]
	v_min_i32_e32 v0, 0x101f, v168
	v_add_co_u32_e32 v10, vcc, s22, v8
	v_add_u32_e32 v0, s10, v0
	v_or_b32_e32 v166, 13, v192
	v_addc_co_u32_e32 v11, vcc, 0, v9, vcc
	v_mad_i64_i32 v[12:13], s[40:41], v0, s96, v[4:5]
	v_min_i32_e32 v0, 0x101f, v166
	v_add_co_u32_e32 v14, vcc, s22, v12
	v_add_u32_e32 v0, s10, v0
	v_or_b32_e32 v164, 14, v192
	v_addc_co_u32_e32 v15, vcc, 0, v13, vcc
	v_mad_i64_i32 v[16:17], s[40:41], v0, s96, v[4:5]
	v_min_i32_e32 v0, 0x101f, v164
	global_load_ushort v174, v[6:7], off
	global_load_ushort v171, v[10:11], off
	global_load_ushort v169, v[14:15], off
	global_load_ushort v106, v[16:17], off offset:1024
	global_load_ushort v110, v[12:13], off offset:1536
; __device__ __forceinline__ void gla_issue_loads(GlaLoads& L, const bf16_t* proj, int b, int h, int n, int dk, int seg, int t4, bool want_q) {
; #pragma unroll
;     for (int i = 0; i < 16; ++i) { const int rb = n * 64 + seg * 16 + i, rc = rb < TB ? rb : TB - 1; const bf16_t* rp = proj + (size_t)(b * TB + rc) * NPROJ + h * 64 + dk;
;         L.xl[i] = rp[C_GL]; L.xk[i] = rp[C_K]; if (want_q) L.xq[i] = rp[C_Q]; }
; #pragma unroll
;     for (int q = 0; q < 4; ++q) { const int task = t4 + 256 * q, dv = task & 127, rg = task >> 7;
; #pragma unroll
;         for (int j = 0; j < 8; ++j) { const int rb = n * 64 + rg * 8 + j, rc = rb < TB ? rb : TB - 1; L.vv[q][j] = proj[(size_t)(b * TB + rc) * NPROJ + C_V + h * 128 + dv]; } }
	global_load_ushort v119, v[12:13], off offset:1024
	global_load_ushort v126, v[8:9], off offset:1536
	global_load_ushort v127, v[8:9], off offset:1024
	v_add_co_u32_e32 v6, vcc, s22, v16
	v_add_u32_e32 v0, s10, v0
	v_or_b32_e32 v162, 15, v192
	v_addc_co_u32_e32 v7, vcc, 0, v17, vcc
	v_mad_i64_i32 v[8:9], s[40:41], v0, s96, v[4:5]
	v_min_i32_e32 v0, 0x101f, v162
	v_add_co_u32_e32 v10, vcc, s22, v8
	v_add_u32_e32 v0, s10, v0
	s_nop 0
	v_addc_co_u32_e32 v11, vcc, 0, v9, vcc
	v_mad_i64_i32 v[4:5], s[40:41], v0, s96, v[4:5]
	v_lshrrev_b32_e32 v0, 4, v71
	v_add_co_u32_e32 v12, vcc, s22, v4
	v_and_or_b32 v3, v0, 8, v70
	s_nop 0
	v_addc_co_u32_e32 v13, vcc, 0, v5, vcc
	global_load_ushort v167, v[6:7], off
	global_load_ushort v165, v[10:11], off
	global_load_ushort v163, v[12:13], off
	global_load_ushort v73, v[4:5], off offset:1536
	global_load_ushort v78, v[4:5], off offset:1024
	global_load_ushort v81, v[8:9], off offset:1536
	global_load_ushort v104, v[8:9], off offset:1024
	global_load_ushort v112, v[16:17], off offset:1536
	v_or_b32_e32 v6, 1, v3
	v_or_b32_e32 v8, 2, v3
	v_or_b32_e32 v10, 3, v3
	v_or_b32_e32 v12, 4, v3
	v_or_b32_e32 v14, 5, v3
	v_or_b32_e32 v16, 6, v3
	v_min_i32_e32 v0, 0x101f, v3
	v_min_i32_e32 v6, 0x101f, v6
	v_min_i32_e32 v8, 0x101f, v8
	v_min_i32_e32 v10, 0x101f, v10
	v_min_i32_e32 v12, 0x101f, v12
	v_min_i32_e32 v14, 0x101f, v14
	v_min_i32_e32 v16, 0x101f, v16
	v_or_b32_e32 v18, 7, v3
	v_add_u32_e32 v0, s10, v0
	v_mov_b64_e32 v[68:69], s[20:21]
	v_add_u32_e32 v6, s10, v6
	v_add_u32_e32 v8, s10, v8
	v_add_u32_e32 v10, s10, v10
	v_add_u32_e32 v12, s10, v12
	v_add_u32_e32 v14, s10, v14
	v_add_u32_e32 v16, s10, v16
	v_min_i32_e32 v18, 0x101f, v18
	v_and_b32_e32 v72, 0x7f, v71
	v_mad_i64_i32 v[4:5], s[40:41], v0, s96, v[68:69]
	s_lshl_b32 s86, s15, 8
	v_mad_i64_i32 v[6:7], s[40:41], v6, s96, v[68:69]
	v_mad_i64_i32 v[8:9], s[40:41], v8, s96, v[68:69]
	v_mad_i64_i32 v[10:11], s[40:41], v10, s96, v[68:69]
	v_mad_i64_i32 v[12:13], s[40:41], v12, s96, v[68:69]
	v_mad_i64_i32 v[14:15], s[40:41], v14, s96, v[68:69]
	v_mad_i64_i32 v[16:17], s[40:41], v16, s96, v[68:69]
	v_add_u32_e32 v18, s10, v18
	v_lshl_add_u64 v[4:5], v[4:5], 0, s[86:87]
	v_lshlrev_b32_e32 v0, 1, v72
	v_lshl_add_u64 v[6:7], v[6:7], 0, s[86:87]
	v_lshl_add_u64 v[8:9], v[8:9], 0, s[86:87]
	v_lshl_add_u64 v[10:11], v[10:11], 0, s[86:87]
	v_lshl_add_u64 v[12:13], v[12:13], 0, s[86:87]
	v_lshl_add_u64 v[14:15], v[14:15], 0, s[86:87]
	v_lshl_add_u64 v[16:17], v[16:17], 0, s[86:87]
	v_mad_i64_i32 v[18:19], s[40:41], v18, s96, v[68:69]
	v_lshl_add_u64 v[4:5], v[4:5], 0, v[0:1]
	v_lshl_add_u64 v[6:7], v[6:7], 0, v[0:1]
	v_lshl_add_u64 v[8:9], v[8:9], 0, v[0:1]
	v_lshl_add_u64 v[10:11], v[10:11], 0, v[0:1]
	v_lshl_add_u64 v[12:13], v[12:13], 0, v[0:1]
	v_lshl_add_u64 v[14:15], v[14:15], 0, v[0:1]
	v_lshl_add_u64 v[16:17], v[16:17], 0, v[0:1]
	v_lshl_add_u64 v[18:19], v[18:19], 0, s[86:87]
	v_lshl_add_u64 v[18:19], v[18:19], 0, v[0:1]
	global_load_ushort v114, v[4:5], off offset:2048
	global_load_ushort v102, v[6:7], off offset:2048
	global_load_ushort v115, v[8:9], off offset:2048
	global_load_ushort v101, v[10:11], off offset:2048
	global_load_ushort v116, v[12:13], off offset:2048
	global_load_ushort v80, v[14:15], off offset:2048
	global_load_ushort v117, v[16:17], off offset:2048
	global_load_ushort v79, v[18:19], off offset:2048
	v_or_b32_e32 v4, 16, v3
	v_or_b32_e32 v6, 17, v3
	v_or_b32_e32 v8, 18, v3
	v_or_b32_e32 v10, 19, v3
	v_or_b32_e32 v12, 20, v3
	v_or_b32_e32 v14, 21, v3
	v_or_b32_e32 v16, 22, v3
	v_min_i32_e32 v4, 0x101f, v4
	v_min_i32_e32 v6, 0x101f, v6
	v_min_i32_e32 v8, 0x101f, v8
	v_min_i32_e32 v10, 0x101f, v10
	v_min_i32_e32 v12, 0x101f, v12
	v_min_i32_e32 v14, 0x101f, v14
	v_min_i32_e32 v16, 0x101f, v16
	v_or_b32_e32 v18, 23, v3
	v_add_u32_e32 v4, s10, v4
	v_add_u32_e32 v6, s10, v6
	v_add_u32_e32 v8, s10, v8
	v_add_u32_e32 v10, s10, v10
	v_add_u32_e32 v12, s10, v12
	v_add_u32_e32 v14, s10, v14
	v_add_u32_e32 v16, s10, v16
	v_min_i32_e32 v18, 0x101f, v18
	v_mad_i64_i32 v[4:5], s[40:41], v4, s96, v[68:69]
	v_mad_i64_i32 v[6:7], s[40:41], v6, s96, v[68:69]
	v_mad_i64_i32 v[8:9], s[40:41], v8, s96, v[68:69]
	v_mad_i64_i32 v[10:11], s[40:41], v10, s96, v[68:69]
	v_mad_i64_i32 v[12:13], s[40:41], v12, s96, v[68:69]
	v_mad_i64_i32 v[14:15], s[40:41], v14, s96, v[68:69]
	v_mad_i64_i32 v[16:17], s[40:41], v16, s96, v[68:69]
	v_add_u32_e32 v18, s10, v18
	v_lshl_add_u64 v[4:5], v[4:5], 0, s[86:87]
	v_lshl_add_u64 v[6:7], v[6:7], 0, s[86:87]
	v_lshl_add_u64 v[8:9], v[8:9], 0, s[86:87]
	v_lshl_add_u64 v[10:11], v[10:11], 0, s[86:87]
	v_lshl_add_u64 v[12:13], v[12:13], 0, s[86:87]
	v_lshl_add_u64 v[14:15], v[14:15], 0, s[86:87]
	v_lshl_add_u64 v[16:17], v[16:17], 0, s[86:87]
	v_mad_i64_i32 v[18:19], s[40:41], v18, s96, v[68:69]
	v_lshl_add_u64 v[4:5], v[4:5], 0, v[0:1]
	v_lshl_add_u64 v[6:7], v[6:7], 0, v[0:1]
	v_lshl_add_u64 v[8:9], v[8:9], 0, v[0:1]
	v_lshl_add_u64 v[10:11], v[10:11], 0, v[0:1]
	v_lshl_add_u64 v[12:13], v[12:13], 0, v[0:1]
	v_lshl_add_u64 v[14:15], v[14:15], 0, v[0:1]
	v_lshl_add_u64 v[16:17], v[16:17], 0, v[0:1]
	v_lshl_add_u64 v[18:19], v[18:19], 0, s[86:87]
	v_lshl_add_u64 v[18:19], v[18:19], 0, v[0:1]
	global_load_ushort v129, v[4:5], off offset:2048
	global_load_ushort v108, v[6:7], off offset:2048
	global_load_ushort v130, v[8:9], off offset:2048
	global_load_ushort v107, v[10:11], off offset:2048
	global_load_ushort v131, v[12:13], off offset:2048
	global_load_ushort v105, v[14:15], off offset:2048
	global_load_ushort v132, v[16:17], off offset:2048
	global_load_ushort v103, v[18:19], off offset:2048
	v_or_b32_e32 v4, 32, v3
; __device__ __forceinline__ void gla_issue_loads(GlaLoads& L, const bf16_t* proj, int b, int h, int n, int dk, int seg, int t4, bool want_q) {
;     ...
;     for (int q = 0; q < 4; ++q) { const int task = t4 + 256 * q, dv = task & 127, rg = task >> 7;
; #pragma unroll
;         for (int j = 0; j < 8; ++j) { const int rb = n * 64 + rg * 8 + j, rc = rb < TB ? rb : TB - 1; L.vv[q][j] = proj[(size_t)(b * TB + rc) * NPROJ + C_V + h * 128 + dv]; } }
; __device__ void gla3_item(const Params& p, int l, int item, LAS unsigned char* lds) {
;     ...
;     const bf16_t* spT = (const bf16_t*)((const unsigned char*)p.out + OS_KVT) + ((size_t)bh * GCH + n) * 8192;
;     bf16x8 spf[8][2];
; #pragma unroll
;     for (int nt = 0; nt < 8; ++nt)
; #pragma unroll
;         for (int ks = 0; ks < 2; ++ks) spf[nt][ks] = *(const bf16x8*)(spT + (nt * 16 + fr) * 64 + ks * 32 + fq * 8);
;     const int rb = n * 64 + wv * 16 + fr, rbc = rb < TB ? rb : TB - 1;
;     bf16_t* rowp = proj + (size_t)(b * TB + rbc) * NPROJ;
;     u32x2 rwv[8];
; #pragma unroll
;     for (int nt = 0; nt < 8; ++nt) rwv[nt] = *(const u32x2*)(rowp + C_R + h * 128 + nt * 16 + 4 * fq);
;     __syncthreads();
	v_or_b32_e32 v6, 33, v3
	v_or_b32_e32 v8, 34, v3
	v_or_b32_e32 v10, 35, v3
	v_or_b32_e32 v12, 36, v3
	v_or_b32_e32 v14, 37, v3
	v_or_b32_e32 v16, 38, v3
	v_min_i32_e32 v4, 0x101f, v4
	v_min_i32_e32 v6, 0x101f, v6
	v_min_i32_e32 v8, 0x101f, v8
	v_min_i32_e32 v10, 0x101f, v10
	v_min_i32_e32 v12, 0x101f, v12
	v_min_i32_e32 v14, 0x101f, v14
	v_min_i32_e32 v16, 0x101f, v16
	v_or_b32_e32 v18, 39, v3
	v_add_u32_e32 v4, s10, v4
	v_add_u32_e32 v6, s10, v6
	v_add_u32_e32 v8, s10, v8
	v_add_u32_e32 v10, s10, v10
	v_add_u32_e32 v12, s10, v12
	v_add_u32_e32 v14, s10, v14
	v_add_u32_e32 v16, s10, v16
	v_min_i32_e32 v18, 0x101f, v18
	v_mad_i64_i32 v[4:5], s[40:41], v4, s96, v[68:69]
	v_mad_i64_i32 v[6:7], s[40:41], v6, s96, v[68:69]
	v_mad_i64_i32 v[8:9], s[40:41], v8, s96, v[68:69]
	v_mad_i64_i32 v[10:11], s[40:41], v10, s96, v[68:69]
	v_mad_i64_i32 v[12:13], s[40:41], v12, s96, v[68:69]
	v_mad_i64_i32 v[14:15], s[40:41], v14, s96, v[68:69]
	v_mad_i64_i32 v[16:17], s[40:41], v16, s96, v[68:69]
	v_add_u32_e32 v18, s10, v18
	v_lshl_add_u64 v[4:5], v[4:5], 0, s[86:87]
	v_lshl_add_u64 v[6:7], v[6:7], 0, s[86:87]
	v_lshl_add_u64 v[8:9], v[8:9], 0, s[86:87]
	v_lshl_add_u64 v[10:11], v[10:11], 0, s[86:87]
	v_lshl_add_u64 v[12:13], v[12:13], 0, s[86:87]
	v_lshl_add_u64 v[14:15], v[14:15], 0, s[86:87]
	v_lshl_add_u64 v[16:17], v[16:17], 0, s[86:87]
	v_mad_i64_i32 v[18:19], s[40:41], v18, s96, v[68:69]
	v_lshl_add_u64 v[4:5], v[4:5], 0, v[0:1]
	v_lshl_add_u64 v[6:7], v[6:7], 0, v[0:1]
	v_lshl_add_u64 v[8:9], v[8:9], 0, v[0:1]
	v_lshl_add_u64 v[10:11], v[10:11], 0, v[0:1]
	v_lshl_add_u64 v[12:13], v[12:13], 0, v[0:1]
	v_lshl_add_u64 v[14:15], v[14:15], 0, v[0:1]
	v_lshl_add_u64 v[16:17], v[16:17], 0, v[0:1]
	v_lshl_add_u64 v[18:19], v[18:19], 0, s[86:87]
	v_lshl_add_u64 v[18:19], v[18:19], 0, v[0:1]
	global_load_ushort v139, v[4:5], off offset:2048
	global_load_ushort v118, v[6:7], off offset:2048
	global_load_ushort v141, v[8:9], off offset:2048
	global_load_ushort v113, v[10:11], off offset:2048
	global_load_ushort v142, v[12:13], off offset:2048
	global_load_ushort v111, v[14:15], off offset:2048
	global_load_ushort v144, v[16:17], off offset:2048
	global_load_ushort v109, v[18:19], off offset:2048
	v_or_b32_e32 v4, 48, v3
	v_or_b32_e32 v6, 49, v3
	v_or_b32_e32 v8, 50, v3
	v_or_b32_e32 v10, 51, v3
	v_or_b32_e32 v12, 52, v3
	v_or_b32_e32 v14, 53, v3
	v_or_b32_e32 v16, 54, v3
	v_or_b32_e32 v3, 55, v3
	v_min_i32_e32 v4, 0x101f, v4
	v_min_i32_e32 v6, 0x101f, v6
	v_min_i32_e32 v8, 0x101f, v8
	v_min_i32_e32 v10, 0x101f, v10
	v_min_i32_e32 v12, 0x101f, v12
	v_min_i32_e32 v14, 0x101f, v14
	v_min_i32_e32 v16, 0x101f, v16
	v_min_i32_e32 v3, 0x101f, v3
	v_add_u32_e32 v4, s10, v4
	v_add_u32_e32 v6, s10, v6
	v_add_u32_e32 v8, s10, v8
	v_add_u32_e32 v10, s10, v10
	v_add_u32_e32 v12, s10, v12
	v_add_u32_e32 v14, s10, v14
	v_add_u32_e32 v16, s10, v16
	v_add_u32_e32 v3, s10, v3
	v_mad_i64_i32 v[4:5], s[40:41], v4, s96, v[68:69]
	v_mad_i64_i32 v[6:7], s[40:41], v6, s96, v[68:69]
	v_mad_i64_i32 v[8:9], s[40:41], v8, s96, v[68:69]
	v_mad_i64_i32 v[10:11], s[40:41], v10, s96, v[68:69]
	v_mad_i64_i32 v[12:13], s[40:41], v12, s96, v[68:69]
	v_mad_i64_i32 v[14:15], s[40:41], v14, s96, v[68:69]
	v_mad_i64_i32 v[16:17], s[40:41], v16, s96, v[68:69]
	v_mad_i64_i32 v[18:19], s[40:41], v3, s96, v[68:69]
	s_mul_i32 s40, s11, 0x42
	s_mov_b32 s41, s87
	v_ashrrev_i32_e32 v3, 31, v2
	v_lshl_add_u64 v[2:3], v[2:3], 0, s[40:41]
	v_lshl_add_u64 v[4:5], v[4:5], 0, s[86:87]
	v_lshlrev_b64 v[2:3], 14, v[2:3]
	v_and_b32_e32 v75, 15, v71
	v_lshl_add_u64 v[4:5], v[4:5], 0, v[0:1]
	v_lshl_add_u64 v[6:7], v[6:7], 0, s[86:87]
	v_lshl_add_u64 v[8:9], v[8:9], 0, s[86:87]
	v_lshl_add_u64 v[10:11], v[10:11], 0, s[86:87]
	v_lshl_add_u64 v[12:13], v[12:13], 0, s[86:87]
	v_lshl_add_u64 v[14:15], v[14:15], 0, s[86:87]
	v_lshl_add_u64 v[16:17], v[16:17], 0, s[86:87]
	v_lshl_add_u64 v[18:19], v[18:19], 0, s[86:87]
	v_lshl_add_u64 v[2:3], s[16:17], 0, v[2:3]
	v_bfe_u32 v240, v228, 6, 2
	v_lshlrev_b32_e32 v240, 12, v240
	v_and_b32_e32 v241, 63, v228
	v_lshl_or_b32 v240, v241, 4, v240
	v_mov_b32_e32 v241, 0
	v_lshl_add_u64 v[242:243], v[2:3], 0, v[240:241]
	v_and_b32_e32 v66, 48, v71
	v_mov_b32_e32 v67, v1
	v_lshl_add_u64 v[6:7], v[6:7], 0, v[0:1]
	v_lshl_add_u64 v[8:9], v[8:9], 0, v[0:1]
	v_lshl_add_u64 v[10:11], v[10:11], 0, v[0:1]
	v_lshl_add_u64 v[12:13], v[12:13], 0, v[0:1]
	v_lshl_add_u64 v[14:15], v[14:15], 0, v[0:1]
	v_lshl_add_u64 v[16:17], v[16:17], 0, v[0:1]
	v_lshl_add_u64 v[18:19], v[18:19], 0, v[0:1]
	global_load_ushort v154, v[4:5], off offset:2048
	global_load_ushort v124, v[6:7], off offset:2048
	global_load_ushort v155, v[8:9], off offset:2048
	global_load_ushort v123, v[10:11], off offset:2048
	global_load_ushort v151, v[12:13], off offset:2048
	global_load_ushort v122, v[14:15], off offset:2048
	global_load_ushort v153, v[16:17], off offset:2048
	global_load_ushort v120, v[18:19], off offset:2048
	v_lshl_add_u64 v[2:3], v[2:3], 0, v[66:67]
	v_lshlrev_b32_e32 v4, 7, v75
	v_mov_b32_e32 v5, v1
	v_lshl_add_u64 v[2:3], v[2:3], 0, v[4:5]
	v_add_co_u32_e32 v4, vcc, s22, v2
	s_movk_i32 s11, 0x2000
	s_nop 0
	v_addc_co_u32_e32 v5, vcc, 0, v3, vcc
	v_add_co_u32_e32 v46, vcc, s11, v2
	s_movk_i32 s11, 0x3000
	s_nop 0
	v_addc_co_u32_e32 v47, vcc, 0, v3, vcc
	global_load_dwordx4 v[204:207], v[242:243], off
	global_load_dwordx4 v[208:211], v[242:243], off offset:1024
	global_load_dwordx4 v[212:215], v[242:243], off offset:2048
	global_load_dwordx4 v[216:219], v[242:243], off offset:3072
	v_add_co_u32_e32 v2, vcc, s11, v2
	v_lshl_or_b32 v77, v74, 4, v75
	s_nop 0
	v_addc_co_u32_e32 v3, vcc, 0, v3, vcc
	v_or_b32_e32 v67, v77, v70
	s_movk_i32 s22, 0x1020
	v_cmp_gt_i32_e32 vcc, s22, v67
	v_mov_b32_e32 v82, 0x101f
	v_bfe_u32 v76, v71, 4, 2
	v_cndmask_b32_e32 v67, v82, v67, vcc
	v_add_u32_e32 v67, s10, v67
	v_mad_i64_i32 v[68:69], s[10:11], v67, s96, v[68:69]
	v_lshlrev_b32_e32 v0, 3, v76
	v_lshl_add_u64 v[68:69], v[68:69], 0, s[86:87]
	v_lshl_add_u64 v[82:83], v[68:69], 0, v[0:1]
	s_nop 0
	s_nop 0
	s_nop 0
	global_load_dwordx2 v[98:99], v[82:83], off offset:3072
	global_load_dwordx2 v[96:97], v[82:83], off offset:3104
	global_load_dwordx2 v[94:95], v[82:83], off offset:3136
	global_load_dwordx2 v[92:93], v[82:83], off offset:3168
	global_load_dwordx2 v[90:91], v[82:83], off offset:3200
	global_load_dwordx2 v[88:89], v[82:83], off offset:3232
	global_load_dwordx2 v[86:87], v[82:83], off offset:3264
	global_load_dwordx2 v[84:85], v[82:83], off offset:3296
	s_add_u32 s10, s3, s86
	s_addc_u32 s11, s18, 0
	v_lshlrev_b32_e32 v100, 2, v149
	s_barrier
; __device__ __forceinline__ float bf2f(bf16_t b) { return __uint_as_float(((unsigned)b) << 16); }
; __device__ __forceinline__ float logsigmoidf_(float x) { return fminf(x, 0.f) - __logf(1.0f + __expf(-fabsf(x))); }
; __device__ __forceinline__ float gla_cumsum(const Params& p, int l, const GlaLoads& L, int h, int n, int dk, int seg, LAS unsigned char* hl, float (&bc)[16]) {
;     const float ba = p.b_alpha[(size_t)l * 256 + h * 64 + dk]; float run = 0.f;
; #pragma unroll
;     for (int i = 0; i < 16; ++i) { const int rb = n * 64 + seg * 16 + i; const float la = rb < TB ? logsigmoidf_(bf2f(L.xl[i]) + ba) * (1.0f / 16.0f) : 0.f;
;         run += la; bc[i] = run; }
	s_waitcnt vmcnt(44)
	v_mov_b32_e32 v69, v251
	s_movk_i32 s15, 0x1020
	v_cmp_gt_i32_e64 s[40:41], s22, v192
	v_mov_b32_e32 v67, 0
	v_mov_b32_e32 v68, 0
	s_and_saveexec_b64 s[10:11], s[40:41]
	s_cbranch_execz .LBB0_452
	v_lshlrev_b32_e32 v68, 16, v193
	v_add_f32_e32 v68, v69, v68
	s_mov_b32 s22, 0xbfb8aa3b
	v_mul_f32_e64 v192, |v68|, s22
	v_exp_f32_e32 v192, v192
	s_mov_b32 s22, 0x800000
	v_min_f32_e32 v68, 0, v68
	v_add_f32_e32 v192, 1.0, v192
	v_cmp_gt_f32_e64 s[42:43], s22, v192
	s_mov_b32 s22, 0x3f317217
	s_nop 0
	v_cndmask_b32_e64 v193, 0, 32, s[42:43]
	v_ldexp_f32 v192, v192, v193
	v_log_f32_e32 v192, v192
	s_nop 0
	v_mul_f32_e32 v193, 0x3f317217, v192
	v_fma_f32 v193, v192, s22, -v193
	v_fmac_f32_e32 v193, 0x3377d1cf, v192
	s_mov_b32 s22, 0x7f800000
	v_fmac_f32_e32 v193, 0x3f317217, v192
	v_cmp_lt_f32_e64 s[44:45], |v192|, s22
	s_mov_b32 s22, 0x3d800000
	s_nop 0
	v_cndmask_b32_e64 v192, v192, v193, s[44:45]
	v_cndmask_b32_e64 v193, 0, v236, s[42:43]
	v_sub_f32_e32 v192, v192, v193
	v_sub_f32_e32 v68, v68, v192
	v_fma_f32 v68, v68, s22, 0

; #define LAS __attribute__((address_space(3)))
; __device__ __forceinline__ float bf2f(bf16_t b) { return __uint_as_float(((unsigned)b) << 16); }
; __device__ __forceinline__ bf16_t f2bf(float f) { return (bf16_t)(cvt_pk_bf16(f, 0.f) & 0xffffu); }
; __device__ __forceinline__ float gla_cumsum(const Params& p, int l, const GlaLoads& L, int h, int n, int dk, int seg, LAS unsigned char* hl, float (&bc)[16]) {
;     ...
;     LAS float* segs = (LAS float*)(hl + GL_SEG);
;     segs[seg * 64 + dk] = run;
;     __syncthreads();
;     float pre = 0.f, tot = 0.f;
; #pragma unroll
;     for (int s = 0; s < 4; ++s) { const float v = segs[s * 64 + dk]; tot += v; if (s < seg) pre += v; }
; #pragma unroll
;     for (int i = 0; i < 16; ++i) bc[i] += pre;
; __device__ void gla3_item(const Params& p, int l, int item, LAS unsigned char* lds) {
;     ...
;     for (int i = 0; i < 16; ++i) { const int rbi = n * 64 + seg * 16 + i, row = seg * 16 + i;
;         const float qv = rbi < TB ? bf2f(L.xq[i]) * 0.125f * __expf(bc[i]) : 0.f, kv = rbi < TB ? bf2f(L.xk[i]) * __expf(-bc[i]) : 0.f;
;         *(LAS bf16_t*)(hl + GL_QD + row * 144 + dk * 2) = f2bf(qv); *(LAS bf16_t*)(hl + GL_KI + row * 144 + dk * 2) = f2bf(kv); }
.LBB0_482:
	s_or_b64 exec, exec, s[10:11]
	v_add_f32_e32 v187, v68, v67
	v_add_f32_e32 v181, v187, v189
	v_add_f32_e32 v179, v181, v188
	v_add_f32_e32 v177, v179, v186
	v_add_f32_e32 v171, v177, v184
	v_add_f32_e32 v170, v171, v182
	v_add_f32_e32 v169, v170, v180
	v_add_f32_e32 v168, v169, v178
	v_add_f32_e32 v167, v168, v176
	v_add_f32_e32 v166, v167, v173
	v_add_f32_e32 v165, v166, v172
	s_waitcnt vmcnt(0)
	v_lshrrev_b32_e32 v240, 8, v228
	v_mul_u32_u24_e32 v240, 0x4800, v240
	v_add_u32_e32 v240, 0x17000, v240
	v_bfe_u32 v241, v228, 6, 2
	v_lshlrev_b32_e32 v241, 5, v241
	v_bfe_u32 v244, v228, 3, 3
	v_add_u32_e32 v241, v241, v244
	v_mul_u32_u24_e32 v241, 0x90, v241
	v_and_b32_e32 v244, 7, v228
	v_lshl_add_u32 v241, v244, 4, v241
	v_add_u32_e32 v244, v240, v241
	v_and_b32_e32 v241, 15, v228
	v_mul_u32_u24_e32 v241, 0x90, v241
	v_bfe_u32 v245, v228, 4, 2
	v_lshl_add_u32 v241, v245, 4, v241
	v_add_u32_e32 v245, v240, v241
	ds_write_b128 v244, v[204:207]
	ds_write_b128 v244, v[208:211] offset:1152
	ds_write_b128 v244, v[212:215] offset:2304
	ds_write_b128 v244, v[216:219] offset:3456
	v_mul_i32_i24_e32 v69, 0xb800, v160
	v_add_f32_e32 v164, v165, v175
	v_add_f32_e32 v163, v164, v174
	v_add_u32_e32 v67, 0, v69
	v_add_f32_e32 v162, v163, v183
	v_lshl_add_u32 v160, v149, 2, v67
	v_add_f32_e32 v69, v162, v185
	v_lshl_add_u32 v172, v74, 8, v160
	ds_write_b32 v172, v69 offset:46080
	s_waitcnt lgkmcnt(0)
	s_barrier
	ds_read2st64_b32 v[172:173], v160 offset0:180 offset1:181
	ds_read_b32 v160, v160 offset:46592
	v_cmp_gt_u32_sdwa s[74:75], v71, v237 src0_sel:BYTE_0 src1_sel:DWORD
	s_movk_i32 s10, 0x7f
	s_waitcnt lgkmcnt(1)
	v_add_f32_e32 v172, 0, v172
	v_cndmask_b32_e64 v172, 0, v172, s[74:75]
	v_add_f32_e32 v173, v173, v172
	v_cmp_gt_u32_sdwa s[74:75], v71, s10 src0_sel:BYTE_0 src1_sel:DWORD
	s_nop 1
	v_cndmask_b32_e64 v172, v172, v173, s[74:75]
	s_waitcnt lgkmcnt(0)
	v_add_f32_e32 v160, v160, v172
	v_cmp_eq_u32_e64 s[74:75], 3, v74
	v_mov_b32_e32 v173, 0
	s_nop 0
	v_cndmask_b32_e64 v160, v172, v160, s[74:75]
	v_add_f32_e32 v68, v68, v160
	v_mov_b32_e32 v172, 0
	s_and_saveexec_b64 s[10:11], s[40:41]
	v_mul_f32_e32 v173, 0x3fb8aa3b, v68
	v_exp_f32_e32 v173, v173
	v_lshlrev_b32_e32 v161, 16, v161
	v_mul_f32_e32 v161, 0x3e000000, v161
	v_mul_f32_e32 v161, v161, v173
	v_cvt_pk_bf16_f32 v173, v161, s0
	s_or_b64 exec, exec, s[10:11]
	v_mul_f32_e32 v68, 0xbfb8aa3b, v68
	v_exp_f32_e32 v174, v68
	v_lshl_add_u32 v68, v149, 1, v67
	v_lshlrev_b32_e32 v149, 16, v159
	s_movk_i32 s10, 0x900
	v_mul_f32_e32 v149, v174, v149
	v_add_f32_e32 v161, v187, v160
	v_cvt_pk_bf16_f32 v149, v149, s0
	v_mad_u32_u24 v159, v74, s10, v68
	v_cndmask_b32_e64 v149, 0, v149, s[40:41]
	ds_write_b16 v159, v173
	ds_write_b16 v159, v149 offset:9216
	s_and_saveexec_b64 s[10:11], s[42:43]
	v_mul_f32_e32 v149, 0x3fb8aa3b, v161
	v_exp_f32_e32 v149, v149
	v_lshlrev_b32_e32 v158, 16, v158
	v_mul_f32_e32 v158, 0x3e000000, v158
	v_mul_f32_e32 v149, v158, v149
	v_cvt_pk_bf16_f32 v172, v149, s0
	s_or_b64 exec, exec, s[10:11]
	v_mul_f32_e32 v149, 0xbfb8aa3b, v161
	v_exp_f32_e32 v149, v149
	v_lshlrev_b32_e32 v157, 16, v157
	v_mul_u32_u24_e32 v159, 0x900, v74
	v_add_u32_e32 v68, v68, v159
	v_mul_f32_e32 v149, v149, v157
	v_cvt_pk_bf16_f32 v149, v149, s0
	v_cndmask_b32_e64 v149, 0, v149, s[42:43]
	v_add_f32_e32 v158, v181, v160
	ds_write_b16 v68, v172 offset:144
	ds_write_b16 v68, v149 offset:9360
	v_mov_b32_e32 v149, 0
	v_mov_b32_e32 v157, 0
	s_and_saveexec_b64 s[10:11], s[44:45]
	v_mul_f32_e32 v157, 0x3fb8aa3b, v158
	v_exp_f32_e32 v157, v157
	v_lshlrev_b32_e32 v150, 16, v150
	v_mul_f32_e32 v150, 0x3e000000, v150
	v_mul_f32_e32 v150, v150, v157
	v_cvt_pk_bf16_f32 v157, v150, s0
	s_or_b64 exec, exec, s[10:11]
	v_mul_f32_e32 v150, 0xbfb8aa3b, v158
	v_exp_f32_e32 v158, v150
	v_lshlrev_b32_e32 v148, 16, v148
	v_add_f32_e32 v150, v179, v160
	v_mul_f32_e32 v148, v158, v148
	v_cvt_pk_bf16_f32 v148, v148, s0
	v_cndmask_b32_e64 v148, 0, v148, s[44:45]
	ds_write_b16 v68, v157 offset:288
	ds_write_b16 v68, v148 offset:9504
	s_and_saveexec_b64 s[10:11], s[46:47]
	v_mul_f32_e32 v148, 0x3fb8aa3b, v150
	v_exp_f32_e32 v148, v148
	v_lshlrev_b32_e32 v149, 16, v156
	v_mul_f32_e32 v149, 0x3e000000, v149
	v_mul_f32_e32 v148, v149, v148
	v_cvt_pk_bf16_f32 v149, v148, s0
	s_or_b64 exec, exec, s[10:11]
	v_mul_f32_e32 v148, 0xbfb8aa3b, v150
	v_exp_f32_e32 v148, v148
	v_lshlrev_b32_e32 v152, 16, v152
	v_add_f32_e32 v150, v177, v160
	ds_write_b16 v68, v149 offset:432
	v_mul_f32_e32 v148, v148, v152
	v_cvt_pk_bf16_f32 v148, v148, s0
	v_cndmask_b32_e64 v148, 0, v148, s[46:47]
	ds_write_b16 v68, v148 offset:9648
	v_mov_b32_e32 v148, 0
	v_mov_b32_e32 v149, 0
	s_and_saveexec_b64 s[10:11], s[48:49]
	v_mul_f32_e32 v149, 0x3fb8aa3b, v150
	v_exp_f32_e32 v149, v149
	v_lshlrev_b32_e32 v147, 16, v147
	v_mul_f32_e32 v147, 0x3e000000, v147
	v_mul_f32_e32 v147, v147, v149
	v_cvt_pk_bf16_f32 v149, v147, s0
	s_or_b64 exec, exec, s[10:11]
	v_mul_f32_e32 v147, 0xbfb8aa3b, v150
	v_exp_f32_e32 v150, v147
	v_lshlrev_b32_e32 v145, 16, v145
	v_add_f32_e32 v147, v171, v160
	v_mul_f32_e32 v145, v150, v145
	v_cvt_pk_bf16_f32 v145, v145, s0
	v_cndmask_b32_e64 v145, 0, v145, s[48:49]
	ds_write_b16 v68, v149 offset:576
	ds_write_b16 v68, v145 offset:9792
	s_and_saveexec_b64 s[10:11], s[50:51]
	v_mul_f32_e32 v145, 0x3fb8aa3b, v147
	v_exp_f32_e32 v145, v145
	v_lshlrev_b32_e32 v143, 16, v143
	v_mul_f32_e32 v143, 0x3e000000, v143
	v_mul_f32_e32 v143, v143, v145
	v_cvt_pk_bf16_f32 v148, v143, s0
	s_or_b64 exec, exec, s[10:11]
	v_mul_f32_e32 v143, 0xbfb8aa3b, v147
	v_exp_f32_e32 v143, v143
	v_lshlrev_b32_e32 v146, 16, v146
	v_add_f32_e32 v145, v170, v160
; #define LAS __attribute__((address_space(3)))
; __device__ __forceinline__ float bf2f(bf16_t b) { return __uint_as_float(((unsigned)b) << 16); }
; __device__ __forceinline__ bf16_t f2bf(float f) { return (bf16_t)(cvt_pk_bf16(f, 0.f) & 0xffffu); }
; __device__ void gla3_item(const Params& p, int l, int item, LAS unsigned char* lds) {
;     ...
;     for (int i = 0; i < 16; ++i) { const int rbi = n * 64 + seg * 16 + i, row = seg * 16 + i;
;         const float qv = rbi < TB ? bf2f(L.xq[i]) * 0.125f * __expf(bc[i]) : 0.f, kv = rbi < TB ? bf2f(L.xk[i]) * __expf(-bc[i]) : 0.f;
;         *(LAS bf16_t*)(hl + GL_QD + row * 144 + dk * 2) = f2bf(qv); *(LAS bf16_t*)(hl + GL_KI + row * 144 + dk * 2) = f2bf(kv); }
	ds_write_b16 v68, v148 offset:720
	v_mul_f32_e32 v143, v143, v146
	v_cvt_pk_bf16_f32 v143, v143, s0
	v_cndmask_b32_e64 v143, 0, v143, s[50:51]
	ds_write_b16 v68, v143 offset:9936
	v_mov_b32_e32 v143, 0
	v_mov_b32_e32 v146, 0
	s_and_saveexec_b64 s[10:11], s[52:53]
	v_mul_f32_e32 v146, 0x3fb8aa3b, v145
	v_exp_f32_e32 v146, v146
	v_lshlrev_b32_e32 v140, 16, v140
	v_mul_f32_e32 v140, 0x3e000000, v140
	v_mul_f32_e32 v140, v140, v146
	v_cvt_pk_bf16_f32 v146, v140, s0
	s_or_b64 exec, exec, s[10:11]
	v_mul_f32_e32 v140, 0xbfb8aa3b, v145
	v_exp_f32_e32 v145, v140
	v_lshlrev_b32_e32 v138, 16, v138
	v_add_f32_e32 v140, v169, v160
	v_mul_f32_e32 v138, v145, v138
	v_cvt_pk_bf16_f32 v138, v138, s0
	v_cndmask_b32_e64 v138, 0, v138, s[52:53]
	ds_write_b16 v68, v146 offset:864
	ds_write_b16 v68, v138 offset:10080
	s_and_saveexec_b64 s[10:11], s[54:55]
	v_mul_f32_e32 v138, 0x3fb8aa3b, v140
	v_exp_f32_e32 v138, v138
	v_lshlrev_b32_e32 v136, 16, v136
	v_mul_f32_e32 v136, 0x3e000000, v136
	v_mul_f32_e32 v136, v136, v138
	v_cvt_pk_bf16_f32 v143, v136, s0
	s_or_b64 exec, exec, s[10:11]
	v_mul_f32_e32 v136, 0xbfb8aa3b, v140
	v_exp_f32_e32 v138, v136
	v_lshlrev_b32_e32 v134, 16, v134
	v_add_f32_e32 v136, v168, v160
	ds_write_b16 v68, v143 offset:1008
	v_mul_f32_e32 v134, v138, v134
	v_cvt_pk_bf16_f32 v134, v134, s0
	v_cndmask_b32_e64 v134, 0, v134, s[54:55]
	ds_write_b16 v68, v134 offset:10224
	v_mov_b32_e32 v134, 0
	v_mov_b32_e32 v138, 0
	s_and_saveexec_b64 s[10:11], s[56:57]
	v_mul_f32_e32 v138, 0x3fb8aa3b, v136
	v_exp_f32_e32 v138, v138
	v_lshlrev_b32_e32 v137, 16, v137
	v_mul_f32_e32 v137, 0x3e000000, v137
	v_mul_f32_e32 v137, v137, v138
	v_cvt_pk_bf16_f32 v138, v137, s0
	s_or_b64 exec, exec, s[10:11]
	v_mul_f32_e32 v136, 0xbfb8aa3b, v136
	v_exp_f32_e32 v137, v136
	v_lshlrev_b32_e32 v135, 16, v135
	v_add_f32_e32 v136, v167, v160
	v_mul_f32_e32 v135, v137, v135
	v_cvt_pk_bf16_f32 v135, v135, s0
	v_cndmask_b32_e64 v135, 0, v135, s[56:57]
	ds_write_b16 v68, v138 offset:1152
	ds_write_b16 v68, v135 offset:10368
	s_and_saveexec_b64 s[10:11], s[58:59]
	v_mul_f32_e32 v134, 0x3fb8aa3b, v136
	v_exp_f32_e32 v134, v134
	v_lshlrev_b32_e32 v133, 16, v133
	v_mul_f32_e32 v133, 0x3e000000, v133
	v_mul_f32_e32 v133, v133, v134
	v_cvt_pk_bf16_f32 v134, v133, s0
	s_or_b64 exec, exec, s[10:11]
	v_mul_f32_e32 v133, 0xbfb8aa3b, v136
	v_exp_f32_e32 v135, v133
	v_lshlrev_b32_e32 v128, 16, v128
	v_add_f32_e32 v133, v166, v160
	ds_write_b16 v68, v134 offset:1296
	v_mul_f32_e32 v128, v135, v128
	v_cvt_pk_bf16_f32 v128, v128, s0
	v_cndmask_b32_e64 v128, 0, v128, s[58:59]
	ds_write_b16 v68, v128 offset:10512
	v_mov_b32_e32 v128, 0
	v_mov_b32_e32 v134, 0
	s_and_saveexec_b64 s[10:11], s[60:61]
	v_mul_f32_e32 v134, 0x3fb8aa3b, v133
	v_exp_f32_e32 v134, v134
	v_lshlrev_b32_e32 v125, 16, v125
	v_mul_f32_e32 v125, 0x3e000000, v125
	v_mul_f32_e32 v125, v125, v134
	v_cvt_pk_bf16_f32 v134, v125, s0
	s_or_b64 exec, exec, s[10:11]
	v_mul_f32_e32 v125, 0xbfb8aa3b, v133
	v_exp_f32_e32 v133, v125
	v_lshlrev_b32_e32 v121, 16, v121
	v_add_f32_e32 v125, v165, v160
	v_mul_f32_e32 v121, v133, v121
	v_cvt_pk_bf16_f32 v121, v121, s0
	v_cndmask_b32_e64 v121, 0, v121, s[60:61]
	ds_write_b16 v68, v134 offset:1440
	ds_write_b16 v68, v121 offset:10656
	s_and_saveexec_b64 s[10:11], s[62:63]
	v_mul_f32_e32 v121, 0x3fb8aa3b, v125
	v_exp_f32_e32 v121, v121
	v_lshlrev_b32_e32 v127, 16, v127
	v_mul_f32_e32 v127, 0x3e000000, v127
	v_mul_f32_e32 v121, v127, v121
	v_cvt_pk_bf16_f32 v128, v121, s0
	s_or_b64 exec, exec, s[10:11]
	v_mul_f32_e32 v121, 0xbfb8aa3b, v125
	v_exp_f32_e32 v121, v121
	v_lshlrev_b32_e32 v126, 16, v126
	v_add_f32_e32 v125, v164, v160
	ds_write_b16 v68, v128 offset:1584
	v_mul_f32_e32 v121, v121, v126
	v_cvt_pk_bf16_f32 v121, v121, s0
	v_cndmask_b32_e64 v121, 0, v121, s[62:63]
	ds_write_b16 v68, v121 offset:10800
	v_mov_b32_e32 v121, 0
	v_mov_b32_e32 v126, 0
	s_and_saveexec_b64 s[10:11], s[64:65]
	v_mul_f32_e32 v126, 0x3fb8aa3b, v125
	v_exp_f32_e32 v126, v126
	v_lshlrev_b32_e32 v119, 16, v119
	v_mul_f32_e32 v119, 0x3e000000, v119
	v_mul_f32_e32 v119, v119, v126
	v_cvt_pk_bf16_f32 v126, v119, s0
	s_or_b64 exec, exec, s[10:11]
	v_mul_f32_e32 v119, 0xbfb8aa3b, v125
	v_exp_f32_e32 v125, v119
	v_lshlrev_b32_e32 v110, 16, v110
	v_add_f32_e32 v119, v163, v160
	v_mul_f32_e32 v110, v125, v110
	v_cvt_pk_bf16_f32 v110, v110, s0
	v_cndmask_b32_e64 v110, 0, v110, s[64:65]
	ds_write_b16 v68, v126 offset:1728
	ds_write_b16 v68, v110 offset:10944
	s_and_saveexec_b64 s[10:11], s[66:67]
	v_mul_f32_e32 v110, 0x3fb8aa3b, v119
	v_exp_f32_e32 v110, v110
	v_lshlrev_b32_e32 v106, 16, v106
	v_mul_f32_e32 v106, 0x3e000000, v106
	v_mul_f32_e32 v106, v106, v110
	v_cvt_pk_bf16_f32 v121, v106, s0
	s_or_b64 exec, exec, s[10:11]
	v_mul_f32_e32 v106, 0xbfb8aa3b, v119
	v_exp_f32_e32 v106, v106
	v_lshlrev_b32_e32 v112, 16, v112
	v_add_f32_e32 v110, v162, v160
	ds_write_b16 v68, v121 offset:1872
	v_mul_f32_e32 v106, v106, v112
	v_cvt_pk_bf16_f32 v106, v106, s0
	v_cndmask_b32_e64 v106, 0, v106, s[66:67]
	ds_write_b16 v68, v106 offset:11088
	v_mov_b32_e32 v106, 0
	v_mov_b32_e32 v112, 0
	s_and_saveexec_b64 s[10:11], s[70:71]
	v_mul_f32_e32 v112, 0x3fb8aa3b, v110
	v_exp_f32_e32 v112, v112
	v_lshlrev_b32_e32 v104, 16, v104
	v_mul_f32_e32 v104, 0x3e000000, v104
	v_mul_f32_e32 v104, v104, v112
	v_cvt_pk_bf16_f32 v112, v104, s0
	s_or_b64 exec, exec, s[10:11]
	v_mul_f32_e32 v104, 0xbfb8aa3b, v110
	v_exp_f32_e32 v104, v104
	v_lshlrev_b32_e32 v81, 16, v81
	v_add_f32_e32 v69, v69, v160
	v_mul_f32_e32 v81, v104, v81
	v_cvt_pk_bf16_f32 v81, v81, s0
	v_cndmask_b32_e64 v81, 0, v81, s[70:71]
	ds_write_b16 v68, v112 offset:2016
	ds_write_b16 v68, v81 offset:11232
; #define LAS __attribute__((address_space(3)))
; __device__ __forceinline__ void gla_store_vT(const GlaLoads& L, int n, int t4, LAS unsigned char* hl) {
; #pragma unroll
;     for (int q = 0; q < 4; ++q) { const int task = t4 + 256 * q, dv = task & 127, rg = task >> 7; unsigned v[8];
; #pragma unroll
;         for (int j = 0; j < 8; ++j) { const int rb = n * 64 + rg * 8 + j; v[j] = rb < TB ? (unsigned)L.vv[q][j] : 0u; }
;         u32x4 w; w.x = v[0] | (v[1] << 16); w.y = v[2] | (v[3] << 16); w.z = v[4] | (v[5] << 16); w.w = v[6] | (v[7] << 16);
;         *(LAS u32x4*)(hl + GL_VT + dv * 144 + rg * 16) = w; }
; }
; __device__ void gla3_item(const Params& p, int l, int item, LAS unsigned char* lds) {
;     ...
;     gla_store_vT(L, n, t4, hl);
;     __syncthreads();
	s_and_saveexec_b64 s[10:11], s[68:69]
	v_mul_f32_e32 v81, 0x3fb8aa3b, v69
	v_exp_f32_e32 v81, v81
	v_lshlrev_b32_e32 v78, 16, v78
	v_mul_f32_e32 v78, 0x3e000000, v78
	v_mul_f32_e32 v78, v78, v81
	v_cvt_pk_bf16_f32 v106, v78, s0
	s_or_b64 exec, exec, s[10:11]
	v_mul_f32_e32 v69, 0xbfb8aa3b, v69
	v_exp_f32_e32 v69, v69
	v_lshlrev_b32_e32 v73, 16, v73
	s_movk_i32 s10, 0x1020
	v_and_b32_e32 v78, 0xffff, v114
	v_mul_f32_e32 v69, v69, v73
	v_cvt_pk_bf16_f32 v69, v69, s0
	v_cndmask_b32_e64 v69, 0, v69, s[68:69]
	ds_write_b16 v68, v106 offset:2160
	ds_write_b16 v68, v69 offset:11376
	v_lshrrev_b32_sdwa v68, v238, v71 dst_sel:DWORD dst_unused:UNUSED_PAD src0_sel:DWORD src1_sel:BYTE_0
	v_lshl_or_b32 v69, v68, 3, v70
	v_cmp_gt_i32_e64 s[40:41], s10, v69
	v_or_b32_e32 v73, 1, v69
	v_and_b32_e32 v81, 0xffff, v115
	v_cndmask_b32_e64 v71, 0, v78, s[40:41]
	v_lshlrev_b32_e32 v78, 16, v102
	v_cmp_gt_i32_e64 s[40:41], s10, v73
	v_lshlrev_b32_e32 v101, 16, v101
	v_and_b32_e32 v104, 0xffff, v116
	v_cndmask_b32_e64 v73, 0, v78, s[40:41]
	v_or_b32_e32 v78, 2, v69
	v_cmp_gt_i32_e64 s[40:41], s10, v78
	v_or_b32_e32 v78, 3, v69
	v_lshlrev_b32_e32 v80, 16, v80
	v_cndmask_b32_e64 v81, 0, v81, s[40:41]
	v_cmp_gt_i32_e64 s[40:41], s10, v78
	v_or_b32_e32 v78, 4, v69
	v_and_b32_e32 v110, 0xffff, v117
	v_cndmask_b32_e64 v101, 0, v101, s[40:41]
	v_cmp_gt_i32_e64 s[40:41], s10, v78
	v_or_b32_e32 v78, 5, v69
	s_movk_i32 s11, 0x90
	v_cndmask_b32_e64 v102, 0, v104, s[40:41]
	v_cmp_gt_i32_e64 s[40:41], s10, v78
	v_or_b32_e32 v78, 6, v69
	v_or_b32_e32 v69, 7, v69
	v_cndmask_b32_e64 v80, 0, v80, s[40:41]
	v_cmp_gt_i32_e64 s[40:41], s10, v78
	v_lshlrev_b32_e32 v78, 16, v79
	v_mad_u32_u24 v72, v72, s11, v67
	v_cndmask_b32_e64 v104, 0, v110, s[40:41]
	v_cmp_gt_i32_e64 s[40:41], s10, v69
	v_or_b32_e32 v79, v101, v81
	v_or_b32_e32 v80, v80, v102
	v_cndmask_b32_e64 v69, 0, v78, s[40:41]
	v_or_b32_e32 v78, v73, v71
	v_or_b32_e32 v81, v69, v104
	v_lshl_add_u32 v69, v68, 4, v72
	ds_write_b128 v69, v[78:81] offset:27648
	v_or_b32_e32 v69, 2, v68
	v_lshl_or_b32 v71, v69, 3, v70
	v_and_b32_e32 v112, 0xffff, v129
	v_cmp_gt_i32_e64 s[40:41], s10, v71
	v_or_b32_e32 v78, 1, v71
	v_lshlrev_b32_e32 v79, 16, v108
	v_cndmask_b32_e64 v73, 0, v112, s[40:41]
	v_cmp_gt_i32_e64 s[40:41], s10, v78
	v_and_b32_e32 v114, 0xffff, v130
	v_or_b32_e32 v80, 3, v71
	v_cndmask_b32_e64 v78, 0, v79, s[40:41]
	v_or_b32_e32 v79, 2, v71
	v_cmp_gt_i32_e64 s[40:41], s10, v79
	v_lshlrev_b32_e32 v81, 16, v107
	v_and_b32_e32 v115, 0xffff, v131
	v_cndmask_b32_e64 v79, 0, v114, s[40:41]
	v_cmp_gt_i32_e64 s[40:41], s10, v80
	v_or_b32_e32 v101, 5, v71
	v_lshlrev_b32_e32 v102, 16, v105
	v_cndmask_b32_e64 v80, 0, v81, s[40:41]
	v_or_b32_e32 v81, 4, v71
	v_cmp_gt_i32_e64 s[40:41], s10, v81
	v_and_b32_e32 v116, 0xffff, v132
	v_lshlrev_b32_e32 v103, 16, v103
	v_cndmask_b32_e64 v81, 0, v115, s[40:41]
	v_cmp_gt_i32_e64 s[40:41], s10, v101
	v_or_b32_e32 v78, v78, v73
	v_or_b32_e32 v79, v80, v79
	v_cndmask_b32_e64 v101, 0, v102, s[40:41]
	v_or_b32_e32 v102, 6, v71
	v_cmp_gt_i32_e64 s[40:41], s10, v102
	v_or_b32_e32 v71, 7, v71
	v_or_b32_e32 v80, v101, v81
	v_cndmask_b32_e64 v102, 0, v116, s[40:41]
	v_cmp_gt_i32_e64 s[40:41], s10, v71
	v_lshl_add_u32 v69, v69, 4, v72
	v_and_b32_e32 v117, 0xffff, v139
	v_cndmask_b32_e64 v71, 0, v103, s[40:41]
	v_or_b32_e32 v81, v71, v102
	ds_write_b128 v69, v[78:81] offset:27648
	v_or_b32_e32 v69, 4, v68
	v_lshl_or_b32 v71, v69, 3, v70
	v_cmp_gt_i32_e64 s[40:41], s10, v71
	v_or_b32_e32 v78, 1, v71
	v_lshlrev_b32_e32 v79, 16, v118
	v_cndmask_b32_e64 v73, 0, v117, s[40:41]
	v_cmp_gt_i32_e64 s[40:41], s10, v78
	v_and_b32_e32 v119, 0xffff, v141
	v_or_b32_e32 v80, 3, v71
	v_cndmask_b32_e64 v78, 0, v79, s[40:41]
	v_or_b32_e32 v79, 2, v71
	v_cmp_gt_i32_e64 s[40:41], s10, v79
	v_lshlrev_b32_e32 v81, 16, v113
	v_and_b32_e32 v121, 0xffff, v142
	v_cndmask_b32_e64 v79, 0, v119, s[40:41]
	v_cmp_gt_i32_e64 s[40:41], s10, v80
	v_or_b32_e32 v101, 5, v71
	v_lshlrev_b32_e32 v102, 16, v111
	v_cndmask_b32_e64 v80, 0, v81, s[40:41]
	v_or_b32_e32 v81, 4, v71
	v_cmp_gt_i32_e64 s[40:41], s10, v81
	v_and_b32_e32 v125, 0xffff, v144
	v_lshlrev_b32_e32 v103, 16, v109
	v_cndmask_b32_e64 v81, 0, v121, s[40:41]
	v_cmp_gt_i32_e64 s[40:41], s10, v101
	v_or_b32_e32 v78, v78, v73
	v_or_b32_e32 v73, 6, v68
	v_cndmask_b32_e64 v101, 0, v102, s[40:41]
	v_or_b32_e32 v102, 6, v71
	v_cmp_gt_i32_e64 s[40:41], s10, v102
	v_or_b32_e32 v71, 7, v71
	v_lshl_or_b32 v68, v73, 3, v70
	v_cndmask_b32_e64 v102, 0, v125, s[40:41]
	v_cmp_gt_i32_e64 s[40:41], s10, v71
	v_and_b32_e32 v126, 0xffff, v154
	v_or_b32_e32 v79, v80, v79
	v_cndmask_b32_e64 v71, 0, v103, s[40:41]
	v_or_b32_e32 v80, v101, v81
	v_or_b32_e32 v81, v71, v102
	v_lshl_add_u32 v69, v69, 4, v72
	v_cmp_gt_i32_e64 s[40:41], s10, v68
	v_or_b32_e32 v70, 1, v68
	ds_write_b128 v69, v[78:81] offset:27648
	v_cndmask_b32_e64 v69, 0, v126, s[40:41]
	v_lshlrev_b32_e32 v71, 16, v124
	v_cmp_gt_i32_e64 s[40:41], s10, v70
	v_and_b32_e32 v127, 0xffff, v155
	v_or_b32_e32 v78, 3, v68
	v_cndmask_b32_e64 v70, 0, v71, s[40:41]
	v_or_b32_e32 v71, 2, v68
	v_cmp_gt_i32_e64 s[40:41], s10, v71
	v_lshlrev_b32_e32 v79, 16, v123
	v_and_b32_e32 v128, 0xffff, v151
	v_cndmask_b32_e64 v71, 0, v127, s[40:41]
	v_cmp_gt_i32_e64 s[40:41], s10, v78
	v_or_b32_e32 v80, 5, v68
	v_lshlrev_b32_e32 v81, 16, v122
	v_cndmask_b32_e64 v78, 0, v79, s[40:41]
	v_or_b32_e32 v79, 4, v68
	v_cmp_gt_i32_e64 s[40:41], s10, v79
	v_and_b32_e32 v129, 0xffff, v153
	v_lshlrev_b32_e32 v101, 16, v120
	v_cndmask_b32_e64 v79, 0, v128, s[40:41]
	v_cmp_gt_i32_e64 s[40:41], s10, v80
	v_lshl_add_u32 v72, v73, 4, v72
	v_add_u32_e32 v103, v67, v66
	v_cndmask_b32_e64 v80, 0, v81, s[40:41]
	v_or_b32_e32 v81, 6, v68
	v_cmp_gt_i32_e64 s[40:41], s10, v81
	v_or_b32_e32 v68, 7, v68
	v_mad_u32_u24 v108, v77, s11, v67
	v_cndmask_b32_e64 v81, 0, v129, s[40:41]
	v_cmp_gt_i32_e64 s[40:41], s10, v68
	v_or_b32_e32 v68, v70, v69
	v_or_b32_e32 v69, v78, v71
	v_cndmask_b32_e64 v101, 0, v101, s[40:41]
	v_or_b32_e32 v70, v80, v79
	v_or_b32_e32 v71, v101, v81
	ds_write_b128 v72, v[68:71] offset:27648
	v_mad_u32_u24 v68, v75, s11, v103
	s_waitcnt lgkmcnt(0)
	s_barrier
; #define LAS __attribute__((address_space(3)))
; __device__ __forceinline__ unsigned cvt_pk_bf16(float lo, float hi) { const f32x2 f = {lo, hi}; const bf16n2 v = __builtin_convertvector(f, bf16n2); return __builtin_bit_cast(unsigned, v); }
; __device__ __forceinline__ f32x4 mfma16(bf16x8 colfrag, bf16x8 rowfrag, f32x4 acc) { return __builtin_amdgcn_mfma_f32_16x16x32_bf16(colfrag, rowfrag, acc, 0, 0, 0); }
; __device__ void gla3_item(const Params& p, int l, int item, LAS unsigned char* lds) {
;     ...
;     bf16x8 qf[2];
; #pragma unroll
;     for (int ks = 0; ks < 2; ++ks) qf[ks] = *(const LAS bf16x8*)(hl + GL_QD + (wv * 16 + fr) * 144 + (ks * 32 + fq * 8) * 2);
; #pragma unroll
;     for (int st = 0; st < 4; ++st) { f32x4 acc = (f32x4){0.f, 0.f, 0.f, 0.f};
;         if (st <= wv) {
; #pragma unroll
;             for (int ks = 0; ks < 2; ++ks) { const bf16x8 cf = *(const LAS bf16x8*)(hl + GL_KI + (st * 16 + fr) * 144 + (ks * 32 + fq * 8) * 2); acc = mfma16(cf, qf[ks], acc); }
;             const int c = wv * 16 + fr, s0 = st * 16 + 4 * fq;
; #pragma unroll
;             for (int r = 0; r < 4; ++r) if (s0 + r > c) acc[r] = 0.f;
;         }
;         u32x2 w; w.x = cvt_pk_bf16(acc[0], acc[1]); w.y = cvt_pk_bf16(acc[2], acc[3]);
;         *(LAS u32x2*)(hl + GL_P + (wv * 16 + fr) * 144 + (st * 16 + 4 * fq) * 2) = w; }
	ds_read_b128 v[78:81], v68 offset:9216
	v_add_u32_e32 v102, v108, v66
	ds_read_b128 v[104:107], v68 offset:9280
	ds_read_b128 v[70:73], v102
	ds_read_b128 v[66:69], v102 offset:64
	s_waitcnt lgkmcnt(1)
	v_mfma_f32_16x16x32_bf16 v[78:81], v[78:81], v[70:73], 0
	v_lshlrev_b32_e32 v101, 2, v76
	v_add_u32_e32 v76, v108, v0
	v_mov_b32_e32 v0, s87
	s_waitcnt lgkmcnt(0)
	v_mfma_f32_16x16x32_bf16 v[78:81], v[104:107], v[66:69], v[78:81]
	v_cmp_gt_u32_e64 s[40:41], v101, v77
	v_or_b32_e32 v104, 2, v101
	v_mul_u32_u24_e32 v108, 0x90, v75
	v_or_b32_e32 v75, 3, v101
	s_nop 3
	v_cndmask_b32_e64 v0, v78, v0, s[40:41]
	v_cmp_lt_u32_e64 s[40:41], v101, v77
	s_nop 1
	v_cndmask_b32_e64 v0, v0, v78, s[40:41]
	v_cndmask_b32_e64 v78, 0, v79, s[40:41]
	v_cmp_le_u32_e64 s[40:41], v104, v77
	v_cvt_pk_bf16_f32 v78, v0, v78
	v_add_u32_e32 v0, v103, v108
	v_cndmask_b32_e64 v79, 0, v80, s[40:41]
	v_cmp_le_u32_e64 s[40:41], v75, v77
	v_mov_b32_e32 v80, 0
	s_nop 0
	v_cndmask_b32_e64 v75, 0, v81, s[40:41]
	v_cvt_pk_bf16_f32 v79, v79, v75
	ds_write_b64 v76, v[78:79] offset:18432
	v_cmp_ne_u32_e64 s[40:41], 0, v74
	v_mov_b32_e32 v75, 0
	v_mov_b32_e32 v78, 0
	v_mov_b32_e32 v79, 0
	v_mov_b32_e32 v81, 0
	s_and_saveexec_b64 s[10:11], s[40:41]
	s_cbranch_execz .LBB0_516
	ds_read_b128 v[78:81], v0 offset:11520
	ds_read_b128 v[104:107], v0 offset:11584
	v_or_b32_e32 v103, 16, v101
	v_cmp_gt_u32_e64 s[40:41], v103, v77
	v_or_b32_e32 v103, 17, v101
	s_waitcnt lgkmcnt(1)
	v_mfma_f32_16x16x32_bf16 v[78:81], v[78:81], v[70:73], 0
	s_waitcnt lgkmcnt(0)
	v_mfma_f32_16x16x32_bf16 v[78:81], v[104:107], v[66:69], v[78:81]
	v_mov_b32_e32 v104, s87
	s_nop 6
	v_cndmask_b32_e64 v78, v78, v104, s[40:41]
	v_cmp_le_u32_e64 s[40:41], v103, v77
	v_or_b32_e32 v103, 18, v101
	s_nop 0
	v_cndmask_b32_e64 v79, 0, v79, s[40:41]
	v_cmp_le_u32_e64 s[40:41], v103, v77
	v_or_b32_e32 v103, 19, v101
	s_nop 0
	v_cndmask_b32_e64 v80, 0, v80, s[40:41]
	v_cmp_le_u32_e64 s[40:41], v103, v77
	s_nop 1
	v_cndmask_b32_e64 v81, 0, v81, s[40:41]

; #define LAS __attribute__((address_space(3)))
; __device__ __forceinline__ f32x4 mfma16(bf16x8 colfrag, bf16x8 rowfrag, f32x4 acc) { return __builtin_amdgcn_mfma_f32_16x16x32_bf16(colfrag, rowfrag, acc, 0, 0, 0); }
; __device__ __forceinline__ float shx(float v, int lane, int o) { return __int_as_float(__builtin_amdgcn_ds_bpermute((lane ^ o) << 2, __float_as_int(v))); }
; __device__ void gla3_item(const Params& p, int l, int item, LAS unsigned char* lds) {
;     ...
;     bf16x8 pf[2];
; #pragma unroll
;     for (int ks = 0; ks < 2; ++ks) pf[ks] = *(const LAS bf16x8*)(hl + GL_P + (wv * 16 + fr) * 144 + (ks * 32 + fq * 8) * 2);
;     f32x4 o[8]; float ss = 0.f;
; #pragma unroll
;     for (int nt = 0; nt < 8; ++nt) { f32x4 acc = (f32x4){0.f, 0.f, 0.f, 0.f};
; #pragma unroll
;         for (int ks = 0; ks < 2; ++ks) { const bf16x8 cf = *(const LAS bf16x8*)(hl + GL_VT + (nt * 16 + fr) * 144 + (ks * 32 + fq * 8) * 2); acc = mfma16(cf, pf[ks], acc); }
;     ...
; #pragma unroll
;         for (int ks = 0; ks < 2; ++ks) acc = mfma16(spf[nt][ks], qf[ks], acc);
;     ...
;         o[nt] = acc; ss += acc[0] * acc[0] + acc[1] * acc[1] + acc[2] * acc[2] + acc[3] * acc[3]; }
;     ss += shx(ss, lane, 16); ss += shx(ss, lane, 32);
.LBB0_520:
	s_or_b64 exec, exec, s[10:11]
	v_cvt_pk_bf16_f32 v74, v75, v74
	v_cvt_pk_bf16_f32 v75, v78, v79
	ds_write_b64 v76, v[74:75] offset:18528
	s_waitcnt lgkmcnt(0)
	s_barrier
	ds_read_b128 v[58:61], v245
	ds_read_b128 v[62:65], v245 offset:64
	ds_read_b128 v[50:53], v245 offset:2304
	ds_read_b128 v[54:57], v245 offset:2368
	ds_read_b128 v[46:49], v245 offset:4608
	ds_read_b128 v[42:45], v245 offset:4672
	ds_read_b128 v[34:37], v245 offset:6912
	ds_read_b128 v[38:41], v245 offset:6976
	ds_read_b128 v[26:29], v245 offset:9216
	ds_read_b128 v[30:33], v245 offset:9280
	ds_read_b128 v[18:21], v245 offset:11520
	ds_read_b128 v[22:25], v245 offset:11584
	ds_read_b128 v[10:13], v245 offset:13824
	ds_read_b128 v[14:17], v245 offset:13888
	ds_read_b128 v[6:9], v245 offset:16128
	ds_read_b128 v[2:5], v245 offset:16192
	ds_read_b128 v[78:81], v102 offset:18432
	ds_read_b128 v[74:77], v102 offset:18496
	ds_read_b128 v[102:105], v0 offset:27648
	ds_read_b128 v[106:109], v0 offset:27712
	s_waitcnt lgkmcnt(1)
	v_mfma_f32_16x16x32_bf16 v[102:105], v[102:105], v[78:81], 0
	s_waitcnt lgkmcnt(0)
	v_mfma_f32_16x16x32_bf16 v[102:105], v[106:109], v[74:77], v[102:105]
	v_mfma_f32_16x16x32_bf16 v[58:61], v[58:61], v[70:73], v[102:105]
	v_mfma_f32_16x16x32_bf16 v[58:61], v[62:65], v[66:69], v[58:61]
	ds_read_b128 v[62:65], v0 offset:29952
	s_nop 4
	ds_read_b128 v[102:105], v0 offset:30016
	s_waitcnt lgkmcnt(1)
	v_mfma_f32_16x16x32_bf16 v[62:65], v[62:65], v[78:81], 0
	v_mul_f32_e32 v106, v59, v59
	v_fmac_f32_e32 v106, v58, v58
	v_fmac_f32_e32 v106, v60, v60
	s_waitcnt lgkmcnt(0)
	v_mfma_f32_16x16x32_bf16 v[62:65], v[102:105], v[74:77], v[62:65]
	v_fmac_f32_e32 v106, v61, v61
	v_mfma_f32_16x16x32_bf16 v[50:53], v[50:53], v[70:73], v[62:65]
	v_mfma_f32_16x16x32_bf16 v[50:53], v[54:57], v[66:69], v[50:53]
	s_nop 4
	ds_read_b128 v[62:65], v0 offset:32320
	s_nop 1
	v_mul_f32_e32 v54, v51, v51
	v_fmac_f32_e32 v54, v50, v50
	v_fmac_f32_e32 v54, v52, v52
	v_fmac_f32_e32 v54, v53, v53
	v_add_f32_e32 v102, v106, v54
	ds_read_b128 v[54:57], v0 offset:32256
	s_waitcnt lgkmcnt(0)
	v_mfma_f32_16x16x32_bf16 v[54:57], v[54:57], v[78:81], 0
	v_mfma_f32_16x16x32_bf16 v[54:57], v[62:65], v[74:77], v[54:57]
	v_mfma_f32_16x16x32_bf16 v[46:49], v[46:49], v[70:73], v[54:57]
	v_mfma_f32_16x16x32_bf16 v[42:45], v[42:45], v[66:69], v[46:49]
	s_nop 5
	ds_read_b128 v[54:57], v0 offset:34624
	s_nop 0
	v_mul_f32_e32 v46, v43, v43
	v_fmac_f32_e32 v46, v42, v42
	v_fmac_f32_e32 v46, v44, v44
	v_fmac_f32_e32 v46, v45, v45
	v_add_f32_e32 v62, v102, v46
	ds_read_b128 v[46:49], v0 offset:34560
	s_waitcnt lgkmcnt(0)
	v_mfma_f32_16x16x32_bf16 v[46:49], v[46:49], v[78:81], 0
	v_mfma_f32_16x16x32_bf16 v[46:49], v[54:57], v[74:77], v[46:49]
	v_mfma_f32_16x16x32_bf16 v[34:37], v[34:37], v[70:73], v[46:49]
	v_mfma_f32_16x16x32_bf16 v[34:37], v[38:41], v[66:69], v[34:37]
	s_nop 5
	ds_read_b128 v[46:49], v0 offset:36928
	s_nop 0
	v_mul_f32_e32 v38, v35, v35
	v_fmac_f32_e32 v38, v34, v34
	v_fmac_f32_e32 v38, v36, v36
	v_fmac_f32_e32 v38, v37, v37
	v_add_f32_e32 v54, v62, v38
	ds_read_b128 v[38:41], v0 offset:36864
	s_waitcnt lgkmcnt(0)
	v_mfma_f32_16x16x32_bf16 v[38:41], v[38:41], v[78:81], 0
	v_mfma_f32_16x16x32_bf16 v[38:41], v[46:49], v[74:77], v[38:41]
	v_mfma_f32_16x16x32_bf16 v[26:29], v[26:29], v[70:73], v[38:41]
	v_mfma_f32_16x16x32_bf16 v[26:29], v[30:33], v[66:69], v[26:29]
	s_nop 5
	ds_read_b128 v[38:41], v0 offset:39232
	s_nop 0
	v_mul_f32_e32 v30, v27, v27
	v_fmac_f32_e32 v30, v26, v26
	v_fmac_f32_e32 v30, v28, v28
	v_fmac_f32_e32 v30, v29, v29
	v_add_f32_e32 v46, v54, v30
	ds_read_b128 v[30:33], v0 offset:39168
	s_waitcnt lgkmcnt(0)
	v_mfma_f32_16x16x32_bf16 v[30:33], v[30:33], v[78:81], 0
	v_mfma_f32_16x16x32_bf16 v[30:33], v[38:41], v[74:77], v[30:33]
	v_mfma_f32_16x16x32_bf16 v[18:21], v[18:21], v[70:73], v[30:33]
	v_mfma_f32_16x16x32_bf16 v[18:21], v[22:25], v[66:69], v[18:21]
	s_nop 5
	ds_read_b128 v[30:33], v0 offset:41536
	s_nop 0
	v_mul_f32_e32 v22, v19, v19
	v_fmac_f32_e32 v22, v18, v18
	v_fmac_f32_e32 v22, v20, v20
	v_fmac_f32_e32 v22, v21, v21
	v_add_f32_e32 v38, v46, v22
	ds_read_b128 v[22:25], v0 offset:41472
	s_waitcnt lgkmcnt(0)
	v_mfma_f32_16x16x32_bf16 v[22:25], v[22:25], v[78:81], 0
	v_mfma_f32_16x16x32_bf16 v[22:25], v[30:33], v[74:77], v[22:25]
	v_mfma_f32_16x16x32_bf16 v[10:13], v[10:13], v[70:73], v[22:25]
	v_mfma_f32_16x16x32_bf16 v[10:13], v[14:17], v[66:69], v[10:13]
	s_nop 5
	ds_read_b128 v[22:25], v0 offset:43840
	s_nop 0
	v_mul_f32_e32 v14, v11, v11
	v_fmac_f32_e32 v14, v10, v10
	v_fmac_f32_e32 v14, v12, v12
	v_fmac_f32_e32 v14, v13, v13
	v_add_f32_e32 v30, v38, v14
	ds_read_b128 v[14:17], v0 offset:43776
	s_waitcnt lgkmcnt(0)
	v_mfma_f32_16x16x32_bf16 v[14:17], v[14:17], v[78:81], 0
	v_mfma_f32_16x16x32_bf16 v[14:17], v[22:25], v[74:77], v[14:17]
	v_mfma_f32_16x16x32_bf16 v[6:9], v[6:9], v[70:73], v[14:17]
	v_mfma_f32_16x16x32_bf16 v[2:5], v[2:5], v[66:69], v[6:9]
	s_nop 6
	v_xor_b32_e32 v6, 64, v100
	v_mul_f32_e32 v0, v3, v3
	v_fmac_f32_e32 v0, v2, v2
	v_fmac_f32_e32 v0, v4, v4
	v_fmac_f32_e32 v0, v5, v5
	v_add_f32_e32 v0, v30, v0
	ds_bpermute_b32 v6, v6, v0
	s_waitcnt lgkmcnt(0)
	v_add_f32_e32 v0, v0, v6
	v_xor_b32_e32 v6, 0x80, v100
	ds_bpermute_b32 v6, v6, v0
	s_and_saveexec_b64 s[10:11], vcc
	s_cbranch_execz .LBB0_522
; __device__ __forceinline__ float bflo(unsigned w) { return __uint_as_float(w << 16); }
; __device__ __forceinline__ float bfhi(unsigned w) { return __uint_as_float(w & 0xffff0000u); }
; __device__ __forceinline__ unsigned cvt_pk_bf16(float lo, float hi) { const f32x2 f = {lo, hi}; const bf16n2 v = __builtin_convertvector(f, bf16n2); return __builtin_bit_cast(unsigned, v); }
; __device__ __forceinline__ float siluf_(float x) { return x * sigmoidf_(x); }
; __device__ __forceinline__ float shx(float v, int lane, int o) { return __int_as_float(__builtin_amdgcn_ds_bpermute((lane ^ o) << 2, __float_as_int(v))); }
; __device__ void gla3_item(const Params& p, int l, int item, LAS unsigned char* lds) {
;     ...
;     ss += shx(ss, lane, 16); ss += shx(ss, lane, 32);
;     const float rstd = rsqrtf(ss * (1.0f / 128.0f) + EPS);
;     if (rb < TB) { const float* gn = p.gla_norm + (size_t)l * 512 + h * 128;
; #pragma unroll
;         for (int nt = 0; nt < 8; ++nt) { const int dv = nt * 16 + 4 * fq; const f32x4 gv = *(const f32x4*)(gn + dv); const u32x2 rw = rwv[nt];
;             const float v0 = o[nt][0] * rstd * gv[0] * siluf_(bflo(rw.x)), v1 = o[nt][1] * rstd * gv[1] * siluf_(bfhi(rw.x)),
;                         v2 = o[nt][2] * rstd * gv[2] * siluf_(bflo(rw.y)), v3 = o[nt][3] * rstd * gv[3] * siluf_(bfhi(rw.y));
;             u32x2 w; w.x = cvt_pk_bf16(v0, v1); w.y = cvt_pk_bf16(v2, v3); if (!p.dry) *(u32x2*)(rowp + C_V + h * 128 + dv) = w; } }
	s_waitcnt lgkmcnt(0)
	v_add_f32_e32 v0, v0, v6
	v_fmamk_f32 v0, v0, 0x3c000000, v229
	s_mov_b32 s15, 0x800000
	v_cmp_gt_f32_e32 vcc, s15, v0
	v_mul_f32_e32 v6, 0x4b800000, v0
	s_lshl_b32 s14, s14, 2
	v_cndmask_b32_e32 v0, v0, v6, vcc
	v_rsq_f32_e32 v0, v0
	s_add_u32 s40, s19, s14
	s_addc_u32 s41, s72, 0
	v_lshlrev_b32_e32 v8, 16, v98
	v_mul_f32_e32 v6, 0x45800000, v0
	v_cndmask_b32_e32 v0, v0, v6, vcc
	v_lshlrev_b32_e32 v6, 2, v101
	v_bfe_u32 v202, v228, 4, 1
	v_mul_u32_u24_e32 v202, 24, v202
	v_mov_b32_e32 v203, 0
	v_lshl_add_u64 v[82:83], v[82:83], 0, v[202:203]
	global_load_dwordx4 v[204:207], v6, s[40:41]
	global_load_dwordx4 v[208:211], v6, s[40:41] offset:64
	global_load_dwordx4 v[212:215], v6, s[40:41] offset:128
	global_load_dwordx4 v[216:219], v6, s[40:41] offset:192
	global_load_dwordx4 v[220:223], v6, s[40:41] offset:256
	global_load_dwordx4 v[224:227], v6, s[40:41] offset:320
	global_load_dwordx4 v[240:243], v6, s[40:41] offset:384
	global_load_dwordx4 v[244:247], v6, s[40:41] offset:448
	v_mul_f32_e32 v7, 0xbfb8aa3b, v8
	v_exp_f32_e32 v7, v7
	v_and_b32_e32 v9, 0xffff0000, v98
	v_pk_mul_f32 v[24:25], v[58:59], v[0:1] op_sel_hi:[1,0]
	v_pk_mul_f32 v[18:19], v[18:19], v[0:1] op_sel_hi:[1,0]
	v_add_f32_e32 v7, 1.0, v7
	v_rcp_f32_e32 v22, v7
	v_mul_f32_e32 v7, 0xbfb8aa3b, v9
	v_exp_f32_e32 v7, v7
	v_pk_mul_f32 v[20:21], v[20:21], v[0:1] op_sel_hi:[1,0]
	v_pk_mul_f32 v[10:11], v[10:11], v[0:1] op_sel_hi:[1,0]
	v_pk_mul_f32 v[12:13], v[12:13], v[0:1] op_sel_hi:[1,0]
	v_add_f32_e32 v7, 1.0, v7
	v_rcp_f32_e32 v23, v7
	v_pk_mul_f32 v[2:3], v[2:3], v[0:1] op_sel_hi:[1,0]
	v_pk_mul_f32 v[4:5], v[4:5], v[0:1] op_sel_hi:[1,0]
	v_pk_mul_f32 v[8:9], v[22:23], v[8:9]
	s_waitcnt vmcnt(0)
	v_pk_mul_f32 v[14:15], v[24:25], v[204:205]
	s_nop 0
	v_pk_mul_f32 v[8:9], v[8:9], v[14:15]
	v_lshlrev_b32_e32 v14, 16, v99
	v_mul_f32_e32 v7, 0xbfb8aa3b, v14
	v_exp_f32_e32 v7, v7
	v_and_b32_e32 v15, 0xffff0000, v99
	v_pk_mul_f32 v[24:25], v[60:61], v[0:1] op_sel_hi:[1,0]
	v_cvt_pk_bf16_f32 v248, v8, v9
	v_add_f32_e32 v7, 1.0, v7
	v_rcp_f32_e32 v22, v7
	v_mul_f32_e32 v7, 0xbfb8aa3b, v15
	v_exp_f32_e32 v7, v7
	v_pk_mul_f32 v[16:17], v[24:25], v[206:207]
	v_pk_mul_f32 v[24:25], v[50:51], v[0:1] op_sel_hi:[1,0]
	v_add_f32_e32 v7, 1.0, v7
	v_rcp_f32_e32 v23, v7
	s_nop 0
	v_pk_mul_f32 v[14:15], v[22:23], v[14:15]
	s_nop 0
	v_pk_mul_f32 v[14:15], v[14:15], v[16:17]
	s_nop 0
	v_cvt_pk_bf16_f32 v249, v14, v15
	v_lshlrev_b32_e32 v8, 16, v96
	v_mul_f32_e32 v7, 0xbfb8aa3b, v8
	v_exp_f32_e32 v7, v7
	v_and_b32_e32 v9, 0xffff0000, v96
	v_add_f32_e32 v7, 1.0, v7
	v_rcp_f32_e32 v22, v7
	v_mul_f32_e32 v7, 0xbfb8aa3b, v9
	v_exp_f32_e32 v7, v7
	v_pk_mul_f32 v[14:15], v[24:25], v[208:209]
	v_add_f32_e32 v7, 1.0, v7
	v_rcp_f32_e32 v23, v7
	v_pk_mul_f32 v[24:25], v[52:53], v[0:1] op_sel_hi:[1,0]
	v_pk_mul_f32 v[8:9], v[22:23], v[8:9]
	s_nop 0
	v_pk_mul_f32 v[8:9], v[8:9], v[14:15]
	v_lshlrev_b32_e32 v14, 16, v97
	v_mul_f32_e32 v7, 0xbfb8aa3b, v14
	v_exp_f32_e32 v7, v7
	v_and_b32_e32 v15, 0xffff0000, v97
	v_pk_mul_f32 v[16:17], v[24:25], v[210:211]
	v_cvt_pk_bf16_f32 v250, v8, v9
	v_add_f32_e32 v7, 1.0, v7
	v_rcp_f32_e32 v22, v7
	v_mul_f32_e32 v7, 0xbfb8aa3b, v15
	v_exp_f32_e32 v7, v7
	v_pk_mul_f32 v[24:25], v[42:43], v[0:1] op_sel_hi:[1,0]
	v_add_f32_e32 v7, 1.0, v7
	v_rcp_f32_e32 v23, v7
	s_nop 0
	v_pk_mul_f32 v[14:15], v[22:23], v[14:15]
	s_nop 0
	v_pk_mul_f32 v[14:15], v[14:15], v[16:17]
	s_nop 0
	v_cvt_pk_bf16_f32 v251, v14, v15
	s_nop 1
	v_permlane16_swap_b32 v248, v250
	v_permlane16_swap_b32 v249, v251
	global_store_dwordx4 v[82:83], v[248:251], off offset:2048
	v_lshlrev_b32_e32 v8, 16, v94
	v_mul_f32_e32 v7, 0xbfb8aa3b, v8
	v_exp_f32_e32 v7, v7
	v_and_b32_e32 v9, 0xffff0000, v94
	v_add_f32_e32 v7, 1.0, v7
	v_rcp_f32_e32 v22, v7
	v_mul_f32_e32 v7, 0xbfb8aa3b, v9
	v_exp_f32_e32 v7, v7
	v_pk_mul_f32 v[14:15], v[24:25], v[212:213]
	v_add_f32_e32 v7, 1.0, v7
	v_rcp_f32_e32 v23, v7
	v_pk_mul_f32 v[24:25], v[44:45], v[0:1] op_sel_hi:[1,0]
	v_pk_mul_f32 v[8:9], v[22:23], v[8:9]
	s_nop 0
	v_pk_mul_f32 v[8:9], v[8:9], v[14:15]
	v_lshlrev_b32_e32 v14, 16, v95
	v_mul_f32_e32 v7, 0xbfb8aa3b, v14
	v_exp_f32_e32 v7, v7
	v_and_b32_e32 v15, 0xffff0000, v95
	v_pk_mul_f32 v[16:17], v[24:25], v[214:215]
	v_cvt_pk_bf16_f32 v248, v8, v9
	v_add_f32_e32 v7, 1.0, v7
	v_rcp_f32_e32 v22, v7
	v_mul_f32_e32 v7, 0xbfb8aa3b, v15
	v_exp_f32_e32 v7, v7
	v_pk_mul_f32 v[24:25], v[34:35], v[0:1] op_sel_hi:[1,0]
	v_add_f32_e32 v7, 1.0, v7
	v_rcp_f32_e32 v23, v7
	s_nop 0
	v_pk_mul_f32 v[14:15], v[22:23], v[14:15]
	s_nop 0
	v_pk_mul_f32 v[14:15], v[14:15], v[16:17]
	s_nop 0
	v_cvt_pk_bf16_f32 v249, v14, v15
	v_lshlrev_b32_e32 v8, 16, v92
	v_mul_f32_e32 v7, 0xbfb8aa3b, v8
	v_exp_f32_e32 v7, v7
	v_and_b32_e32 v9, 0xffff0000, v92
	v_add_f32_e32 v7, 1.0, v7
	v_rcp_f32_e32 v22, v7
	v_mul_f32_e32 v7, 0xbfb8aa3b, v9
	v_exp_f32_e32 v7, v7
	v_pk_mul_f32 v[14:15], v[24:25], v[216:217]
; __device__ __forceinline__ float bflo(unsigned w) { return __uint_as_float(w << 16); }
; __device__ __forceinline__ float bfhi(unsigned w) { return __uint_as_float(w & 0xffff0000u); }
; __device__ __forceinline__ unsigned cvt_pk_bf16(float lo, float hi) { const f32x2 f = {lo, hi}; const bf16n2 v = __builtin_convertvector(f, bf16n2); return __builtin_bit_cast(unsigned, v); }
; __device__ __forceinline__ float siluf_(float x) { return x * sigmoidf_(x); }
; __device__ void gla3_item(const Params& p, int l, int item, LAS unsigned char* lds) {
;     ...
;         for (int nt = 0; nt < 8; ++nt) { const int dv = nt * 16 + 4 * fq; const f32x4 gv = *(const f32x4*)(gn + dv); const u32x2 rw = rwv[nt];
;             const float v0 = o[nt][0] * rstd * gv[0] * siluf_(bflo(rw.x)), v1 = o[nt][1] * rstd * gv[1] * siluf_(bfhi(rw.x)),
;                         v2 = o[nt][2] * rstd * gv[2] * siluf_(bflo(rw.y)), v3 = o[nt][3] * rstd * gv[3] * siluf_(bfhi(rw.y));
;             u32x2 w; w.x = cvt_pk_bf16(v0, v1); w.y = cvt_pk_bf16(v2, v3); if (!p.dry) *(u32x2*)(rowp + C_V + h * 128 + dv) = w; } }
	v_add_f32_e32 v7, 1.0, v7
	v_rcp_f32_e32 v23, v7
	v_pk_mul_f32 v[24:25], v[36:37], v[0:1] op_sel_hi:[1,0]
	v_pk_mul_f32 v[8:9], v[22:23], v[8:9]
	s_nop 0
	v_pk_mul_f32 v[8:9], v[8:9], v[14:15]
	v_lshlrev_b32_e32 v14, 16, v93
	v_mul_f32_e32 v7, 0xbfb8aa3b, v14
	v_exp_f32_e32 v7, v7
	v_and_b32_e32 v15, 0xffff0000, v93
	v_pk_mul_f32 v[16:17], v[24:25], v[218:219]
	v_cvt_pk_bf16_f32 v250, v8, v9
	v_add_f32_e32 v7, 1.0, v7
	v_rcp_f32_e32 v22, v7
	v_mul_f32_e32 v7, 0xbfb8aa3b, v15
	v_exp_f32_e32 v7, v7
	v_pk_mul_f32 v[24:25], v[26:27], v[0:1] op_sel_hi:[1,0]
	v_add_f32_e32 v7, 1.0, v7
	v_rcp_f32_e32 v23, v7
	s_nop 0
	v_pk_mul_f32 v[14:15], v[22:23], v[14:15]
	s_nop 0
	v_pk_mul_f32 v[14:15], v[14:15], v[16:17]
	s_nop 0
	v_cvt_pk_bf16_f32 v251, v14, v15
	s_nop 1
	v_permlane16_swap_b32 v248, v250
	v_permlane16_swap_b32 v249, v251
	global_store_dwordx4 v[82:83], v[248:251], off offset:2112
	v_lshlrev_b32_e32 v8, 16, v90
	v_mul_f32_e32 v7, 0xbfb8aa3b, v8
	v_exp_f32_e32 v7, v7
	v_and_b32_e32 v9, 0xffff0000, v90
	v_add_f32_e32 v7, 1.0, v7
	v_rcp_f32_e32 v22, v7
	v_mul_f32_e32 v7, 0xbfb8aa3b, v9
	v_exp_f32_e32 v7, v7
	v_pk_mul_f32 v[14:15], v[24:25], v[220:221]
	v_add_f32_e32 v7, 1.0, v7
	v_rcp_f32_e32 v23, v7
	v_pk_mul_f32 v[24:25], v[28:29], v[0:1] op_sel_hi:[1,0]
	v_pk_mul_f32 v[8:9], v[22:23], v[8:9]
	s_nop 0
	v_pk_mul_f32 v[8:9], v[8:9], v[14:15]
	v_lshlrev_b32_e32 v14, 16, v91
	v_mul_f32_e32 v7, 0xbfb8aa3b, v14
	v_exp_f32_e32 v7, v7
	v_and_b32_e32 v15, 0xffff0000, v91
	v_pk_mul_f32 v[16:17], v[24:25], v[222:223]
	v_cvt_pk_bf16_f32 v248, v8, v9
	v_add_f32_e32 v7, 1.0, v7
	v_rcp_f32_e32 v22, v7
	v_mul_f32_e32 v7, 0xbfb8aa3b, v15
	v_exp_f32_e32 v7, v7
	s_nop 0
	v_add_f32_e32 v7, 1.0, v7
	v_rcp_f32_e32 v23, v7
	s_nop 0
	v_pk_mul_f32 v[14:15], v[22:23], v[14:15]
	s_nop 0
	v_pk_mul_f32 v[14:15], v[14:15], v[16:17]
	s_nop 0
	v_cvt_pk_bf16_f32 v249, v14, v15
	v_lshlrev_b32_e32 v8, 16, v88
	v_mul_f32_e32 v7, 0xbfb8aa3b, v8
	v_exp_f32_e32 v7, v7
	v_and_b32_e32 v9, 0xffff0000, v88
	v_add_f32_e32 v7, 1.0, v7
	v_rcp_f32_e32 v22, v7
	v_mul_f32_e32 v7, 0xbfb8aa3b, v9
	v_exp_f32_e32 v7, v7
	v_pk_mul_f32 v[14:15], v[18:19], v[224:225]
	v_add_f32_e32 v7, 1.0, v7
	v_rcp_f32_e32 v23, v7
	v_pk_mul_f32 v[16:17], v[20:21], v[226:227]
	v_pk_mul_f32 v[8:9], v[22:23], v[8:9]
	s_nop 0
	v_pk_mul_f32 v[8:9], v[8:9], v[14:15]
	v_lshlrev_b32_e32 v14, 16, v89
	v_mul_f32_e32 v7, 0xbfb8aa3b, v14
	v_exp_f32_e32 v7, v7
	v_and_b32_e32 v15, 0xffff0000, v89
	v_cvt_pk_bf16_f32 v250, v8, v9
	v_add_f32_e32 v7, 1.0, v7
	v_rcp_f32_e32 v18, v7
	v_mul_f32_e32 v7, 0xbfb8aa3b, v15
	v_exp_f32_e32 v7, v7
	s_nop 0
	v_add_f32_e32 v7, 1.0, v7
	v_rcp_f32_e32 v19, v7
	s_nop 0
	v_pk_mul_f32 v[14:15], v[18:19], v[14:15]
	s_nop 0
	v_pk_mul_f32 v[14:15], v[14:15], v[16:17]
	s_nop 0
	v_cvt_pk_bf16_f32 v251, v14, v15
	s_nop 1
	v_permlane16_swap_b32 v248, v250
	v_permlane16_swap_b32 v249, v251
	global_store_dwordx4 v[82:83], v[248:251], off offset:2176
	v_lshlrev_b32_e32 v8, 16, v86
	v_mul_f32_e32 v7, 0xbfb8aa3b, v8
	v_exp_f32_e32 v7, v7
	v_and_b32_e32 v9, 0xffff0000, v86
	v_add_f32_e32 v7, 1.0, v7
	v_rcp_f32_e32 v18, v7
	v_mul_f32_e32 v7, 0xbfb8aa3b, v9
	v_exp_f32_e32 v7, v7
	v_pk_mul_f32 v[10:11], v[10:11], v[240:241]
	v_add_f32_e32 v7, 1.0, v7
	v_rcp_f32_e32 v19, v7
	v_pk_mul_f32 v[12:13], v[12:13], v[242:243]
	v_pk_mul_f32 v[8:9], v[18:19], v[8:9]
	s_nop 0
	v_pk_mul_f32 v[8:9], v[8:9], v[10:11]
	v_lshlrev_b32_e32 v10, 16, v87
	v_mul_f32_e32 v7, 0xbfb8aa3b, v10
	v_exp_f32_e32 v7, v7
	v_and_b32_e32 v11, 0xffff0000, v87
	v_cvt_pk_bf16_f32 v248, v8, v9
	v_add_f32_e32 v7, 1.0, v7
	v_rcp_f32_e32 v14, v7
	v_mul_f32_e32 v7, 0xbfb8aa3b, v11
	v_exp_f32_e32 v7, v7
	s_nop 0
	v_add_f32_e32 v7, 1.0, v7
	v_rcp_f32_e32 v15, v7
	s_nop 0
	v_pk_mul_f32 v[10:11], v[14:15], v[10:11]
	s_nop 0
	v_pk_mul_f32 v[10:11], v[10:11], v[12:13]
	s_nop 0
	v_cvt_pk_bf16_f32 v249, v10, v11
	v_lshlrev_b32_e32 v10, 16, v84
	v_and_b32_e32 v11, 0xffff0000, v84
	v_mul_f32_e32 v12, 0xbfb8aa3b, v10
	v_exp_f32_e32 v12, v12
	v_pk_mul_f32 v[2:3], v[2:3], v[244:245]
	v_mul_f32_e32 v6, 0xbfb8aa3b, v11
	v_exp_f32_e32 v6, v6
	v_add_f32_e32 v12, 1.0, v12
	v_rcp_f32_e32 v12, v12
	v_pk_mul_f32 v[4:5], v[4:5], v[246:247]
	v_add_f32_e32 v6, 1.0, v6
	v_rcp_f32_e32 v13, v6
	s_nop 0
	v_pk_mul_f32 v[6:7], v[12:13], v[10:11]
	s_nop 0
	v_pk_mul_f32 v[2:3], v[6:7], v[2:3]
	v_lshlrev_b32_e32 v6, 16, v85
	v_and_b32_e32 v7, 0xffff0000, v85
	v_cvt_pk_bf16_f32 v250, v2, v3
	v_mul_f32_e32 v3, 0xbfb8aa3b, v6
	v_mul_f32_e32 v0, 0xbfb8aa3b, v7
	v_exp_f32_e32 v3, v3
	v_exp_f32_e32 v0, v0
	v_add_f32_e32 v3, 1.0, v3
	v_add_f32_e32 v0, 1.0, v0
	v_rcp_f32_e32 v10, v3
	v_rcp_f32_e32 v11, v0
	s_nop 0
	v_pk_mul_f32 v[6:7], v[10:11], v[6:7]
	s_nop 0
	v_pk_mul_f32 v[4:5], v[6:7], v[4:5]
	s_nop 0
	v_cvt_pk_bf16_f32 v251, v4, v5
	s_nop 1
	v_permlane16_swap_b32 v248, v250
	v_permlane16_swap_b32 v249, v251
	global_store_dwordx4 v[82:83], v[248:251], off offset:2240
